# hoist the 8 serialized row-scale loads of the Swiglu (x2) and non-rope QKV epilogues to one batch; drop per-group vmcnt(0)
# speedup vs baseline: 1.0161x; 1.0129x over previous
; #define PG8_STAGE(bufoff, gbase, voff) do { _Pragma("unroll") for (int _i = 0; _i < 2; ++_i) \
;         __builtin_amdgcn_global_load_lds((const unsigned*)((const char*)(gbase) + (voff)[_i]), (LAS unsigned*)(lds + (bufoff) + ldsw + _i * 8192), 16, 0, 0); } while (0)
; #define PG8_LDA(dst, b, h) do { _Pragma("unroll") for (int m = 0; m < 4; ++m) _Pragma("unroll") for (int k = 0; k < 2; ++k) dst[m][k] = *(const LAS bf16x8*)(lds + PG8_SA(b, h) + aoff + m * 2048 + k * 1024); } while (0)
; #define PG8_LDB(dst, b, h) do { _Pragma("unroll") for (int n = 0; n < 2; ++n) _Pragma("unroll") for (int k = 0; k < 2; ++k) dst[n][k] = *(const LAS bf16x8*)(lds + PG8_SB(b, h) + boff + n * 2048 + k * 1024); } while (0)
; #define PG8_MMA(ai, bj, At, Bt) do { __builtin_amdgcn_s_setprio(1); _Pragma("unroll") for (int m = 0; m < 4; ++m) _Pragma("unroll") for (int n = 0; n < 2; ++n) _Pragma("unroll") for (int k = 0; k < 2; ++k) \
;         acc[ai][bj][m][n] = __builtin_amdgcn_mfma_f32_16x16x32_bf16(Bt[n][k], At[m][k], acc[ai][bj][m][n], 0, 0, 0); __builtin_amdgcn_s_setprio(0); } while (0)
; #define PG8_WAIT_L(n) asm volatile("s_waitcnt lgkmcnt(" #n ")" ::: "memory")
; #define PG8_BAR __builtin_amdgcn_s_barrier()
; #define PG8_SCHED __builtin_amdgcn_sched_barrier(0)
; template <class Epi>
; __device__ __forceinline__ void gemm_phase(LAS unsigned char* lds, const Gemm g, const StaticOrder& S, const Epi& E) {
;     ...
;             PG8_LDB(B0, 0, 0); PG8_SCHED; PG8_LDA(At, 0, 0); PG8_STAGE(PG8_SA(1, 1), a1 + hstep, voffA);
;             PG8_WAIT_L(8); PG8_BAR; PG8_WAIT_L(0); PG8_MMA(0, 0, At, B0); PG8_BAR; PG8_SCHED;
;             PG8_LDB(B1, 0, 1); PG8_STAGE(PG8_SB(0, 0), b2, voffB);
;             PG8_BAR; PG8_WAIT_L(0); PG8_MMA(0, 1, At, B1); PG8_BAR;
;             PG8_LDA(At, 0, 1); PG8_STAGE(PG8_SA(0, 0), a2, voffA);
;             PG8_BAR; PG8_WAIT_L(0); PG8_MMA(1, 0, At, B0); PG8_BAR; PG8_SCHED;
.LBB0_203:
	ds_read_b128 v[144:147], v153
	ds_read_b128 v[160:163], v153 offset:1024
	ds_read_b128 v[164:167], v153 offset:2048
	ds_read_b128 v[168:171], v153 offset:3072
	s_add_u32 s44, s42, 0xfff80080
	s_addc_u32 s45, s43, -1
	s_cmp_eq_u32 s54, 28
	s_cselect_b32 s47, s25, s45
	s_cselect_b32 s46, s50, s44
	s_cselect_b32 s45, s23, s53
	s_cselect_b32 s44, s51, s52
	v_lshl_add_u64 v[148:149], s[42:43], 0, v[136:137]
	s_add_i32 m0, s11, 0xc000
	ds_read_b128 v[172:175], v154
	ds_read_b128 v[176:179], v154 offset:1024
	ds_read_b128 v[180:183], v154 offset:2048
	ds_read_b128 v[184:187], v154 offset:3072
	ds_read_b128 v[188:191], v154 offset:4096
	ds_read_b128 v[192:195], v154 offset:5120
	ds_read_b128 v[196:199], v154 offset:6144
	ds_read_b128 v[200:203], v154 offset:7168
	global_load_lds_dwordx4 v[148:149], off
	v_lshl_add_u64 v[148:149], s[42:43], 0, v[138:139]
	s_add_i32 m0, s11, 0xe000
	s_nop 0
	global_load_lds_dwordx4 v[148:149], off
	s_waitcnt lgkmcnt(8)
	s_barrier
	s_waitcnt lgkmcnt(0)
	s_setprio 1
	s_waitcnt lgkmcnt(0)
	v_mfma_f32_16x16x32_bf16 v[124:127], v[144:147], v[172:175], v[124:127]
	v_mfma_f32_16x16x32_bf16 v[120:123], v[164:167], v[172:175], v[120:123]
	v_mfma_f32_16x16x32_bf16 v[108:111], v[144:147], v[180:183], v[108:111]
	v_mfma_f32_16x16x32_bf16 v[104:107], v[164:167], v[180:183], v[104:107]
	v_mfma_f32_16x16x32_bf16 v[92:95], v[144:147], v[188:191], v[92:95]
	v_mfma_f32_16x16x32_bf16 v[88:91], v[164:167], v[188:191], v[88:91]
	v_mfma_f32_16x16x32_bf16 v[76:79], v[144:147], v[196:199], v[76:79]
	v_mfma_f32_16x16x32_bf16 v[72:75], v[164:167], v[196:199], v[72:75]
	v_mfma_f32_16x16x32_bf16 v[124:127], v[160:163], v[176:179], v[124:127]
	v_mfma_f32_16x16x32_bf16 v[120:123], v[168:171], v[176:179], v[120:123]
	v_mfma_f32_16x16x32_bf16 v[108:111], v[160:163], v[184:187], v[108:111]
	v_mfma_f32_16x16x32_bf16 v[104:107], v[168:171], v[184:187], v[104:107]
	v_mfma_f32_16x16x32_bf16 v[92:95], v[160:163], v[192:195], v[92:95]
	v_mfma_f32_16x16x32_bf16 v[88:91], v[168:171], v[192:195], v[88:91]
	v_mfma_f32_16x16x32_bf16 v[76:79], v[160:163], v[200:203], v[76:79]
	v_mfma_f32_16x16x32_bf16 v[72:75], v[168:171], v[200:203], v[72:75]
	s_setprio 0
	s_barrier
	s_add_i32 s55, s41, s10
	v_lshl_add_u64 v[148:149], s[44:45], 0, v[132:133]
	s_mov_b32 m0, s55
	ds_read_b128 v[204:207], v155
	ds_read_b128 v[208:211], v155 offset:1024
	ds_read_b128 v[212:215], v155 offset:2048
	ds_read_b128 v[216:219], v155 offset:3072
	global_load_lds_dwordx4 v[148:149], off
	v_lshl_add_u64 v[156:157], s[44:45], 0, v[128:129]
	s_add_i32 m0, s55, 0x2000
	s_nop 0
	global_load_lds_dwordx4 v[156:157], off
	s_barrier
	s_waitcnt lgkmcnt(0)
	s_setprio 1
	s_waitcnt lgkmcnt(0)
	v_mfma_f32_16x16x32_bf16 v[116:119], v[204:207], v[172:175], v[116:119]
	v_mfma_f32_16x16x32_bf16 v[112:115], v[212:215], v[172:175], v[112:115]
	v_mfma_f32_16x16x32_bf16 v[100:103], v[204:207], v[180:183], v[100:103]
	v_mfma_f32_16x16x32_bf16 v[96:99], v[212:215], v[180:183], v[96:99]
	v_mfma_f32_16x16x32_bf16 v[84:87], v[204:207], v[188:191], v[84:87]
	v_mfma_f32_16x16x32_bf16 v[80:83], v[212:215], v[188:191], v[80:83]
	v_mfma_f32_16x16x32_bf16 v[68:71], v[204:207], v[196:199], v[68:71]
	v_mfma_f32_16x16x32_bf16 v[64:67], v[212:215], v[196:199], v[64:67]
	v_mfma_f32_16x16x32_bf16 v[116:119], v[208:211], v[176:179], v[116:119]
	v_mfma_f32_16x16x32_bf16 v[112:115], v[216:219], v[176:179], v[112:115]
	v_mfma_f32_16x16x32_bf16 v[100:103], v[208:211], v[184:187], v[100:103]
	v_mfma_f32_16x16x32_bf16 v[96:99], v[216:219], v[184:187], v[96:99]
	v_mfma_f32_16x16x32_bf16 v[84:87], v[208:211], v[192:195], v[84:87]
	v_mfma_f32_16x16x32_bf16 v[80:83], v[216:219], v[192:195], v[80:83]
	v_mfma_f32_16x16x32_bf16 v[68:71], v[208:211], v[200:203], v[68:71]
	v_mfma_f32_16x16x32_bf16 v[64:67], v[216:219], v[200:203], v[64:67]
	s_setprio 0
	s_mov_b32 m0, s11
	v_lshl_add_u64 v[220:221], s[46:47], 0, v[134:135]
	s_barrier
	ds_read_b128 v[172:175], v154 offset:16384
	ds_read_b128 v[176:179], v154 offset:17408
	ds_read_b128 v[180:183], v154 offset:18432
	ds_read_b128 v[184:187], v154 offset:19456
	ds_read_b128 v[188:191], v154 offset:20480
	ds_read_b128 v[192:195], v154 offset:21504
	ds_read_b128 v[196:199], v154 offset:22528
	ds_read_b128 v[200:203], v154 offset:23552
	global_load_lds_dwordx4 v[220:221], off
	v_lshl_add_u64 v[222:223], s[46:47], 0, v[130:131]
	s_mov_b32 m0, s13
	s_nop 0
	global_load_lds_dwordx4 v[222:223], off
	s_barrier
	s_waitcnt lgkmcnt(0)
	s_setprio 1
	s_waitcnt lgkmcnt(0)
	v_mfma_f32_16x16x32_bf16 v[60:63], v[144:147], v[172:175], v[60:63]
	v_mfma_f32_16x16x32_bf16 v[56:59], v[164:167], v[172:175], v[56:59]
	v_mfma_f32_16x16x32_bf16 v[44:47], v[144:147], v[180:183], v[44:47]
	v_mfma_f32_16x16x32_bf16 v[40:43], v[164:167], v[180:183], v[40:43]
	v_mfma_f32_16x16x32_bf16 v[28:31], v[144:147], v[188:191], v[28:31]
	v_mfma_f32_16x16x32_bf16 v[24:27], v[164:167], v[188:191], v[24:27]
	v_mfma_f32_16x16x32_bf16 v[12:15], v[144:147], v[196:199], v[12:15]
	v_mfma_f32_16x16x32_bf16 v[8:11], v[164:167], v[196:199], v[8:11]
	v_mfma_f32_16x16x32_bf16 v[60:63], v[160:163], v[176:179], v[60:63]
	v_mfma_f32_16x16x32_bf16 v[56:59], v[168:171], v[176:179], v[56:59]
	v_mfma_f32_16x16x32_bf16 v[44:47], v[160:163], v[184:187], v[44:47]
	v_mfma_f32_16x16x32_bf16 v[40:43], v[168:171], v[184:187], v[40:43]
	v_mfma_f32_16x16x32_bf16 v[28:31], v[160:163], v[192:195], v[28:31]
	v_mfma_f32_16x16x32_bf16 v[24:27], v[168:171], v[192:195], v[24:27]
	v_mfma_f32_16x16x32_bf16 v[12:15], v[160:163], v[200:203], v[12:15]
	v_mfma_f32_16x16x32_bf16 v[8:11], v[168:171], v[200:203], v[8:11]
	s_setprio 0
	s_barrier
; #define PG8_STAGE(bufoff, gbase, voff) do { _Pragma("unroll") for (int _i = 0; _i < 2; ++_i) \
;         __builtin_amdgcn_global_load_lds((const unsigned*)((const char*)(gbase) + (voff)[_i]), (LAS unsigned*)(lds + (bufoff) + ldsw + _i * 8192), 16, 0, 0); } while (0)
; #define PG8_LDA(dst, b, h) do { _Pragma("unroll") for (int m = 0; m < 4; ++m) _Pragma("unroll") for (int k = 0; k < 2; ++k) dst[m][k] = *(const LAS bf16x8*)(lds + PG8_SA(b, h) + aoff + m * 2048 + k * 1024); } while (0)
; #define PG8_LDB(dst, b, h) do { _Pragma("unroll") for (int n = 0; n < 2; ++n) _Pragma("unroll") for (int k = 0; k < 2; ++k) dst[n][k] = *(const LAS bf16x8*)(lds + PG8_SB(b, h) + boff + n * 2048 + k * 1024); } while (0)
; #define PG8_MMA(ai, bj, At, Bt) do { __builtin_amdgcn_s_setprio(1); _Pragma("unroll") for (int m = 0; m < 4; ++m) _Pragma("unroll") for (int n = 0; n < 2; ++n) _Pragma("unroll") for (int k = 0; k < 2; ++k) \
;         acc[ai][bj][m][n] = __builtin_amdgcn_mfma_f32_16x16x32_bf16(Bt[n][k], At[m][k], acc[ai][bj][m][n], 0, 0, 0); __builtin_amdgcn_s_setprio(0); } while (0)
; #define PG8_WAIT_V(n) asm volatile("s_waitcnt vmcnt(" #n ")" ::: "memory")
; #define PG8_WAIT_L(n) asm volatile("s_waitcnt lgkmcnt(" #n ")" ::: "memory")
; #define PG8_BAR __builtin_amdgcn_s_barrier()
; #define PG8_SCHED __builtin_amdgcn_sched_barrier(0)
; template <class Epi>
; __device__ __forceinline__ void gemm_phase(LAS unsigned char* lds, const Gemm g, const StaticOrder& S, const Epi& E) {
;     ...
;             PG8_STAGE(PG8_SB(0, 1), b2 + hstep, voffB);
;             PG8_WAIT_V(6); PG8_BAR; PG8_MMA(1, 1, At, B1); PG8_BAR;
;             PG8_LDB(B0, 1, 0); PG8_SCHED; PG8_LDA(At, 1, 0); PG8_STAGE(PG8_SA(0, 1), a2 + hstep, voffA);
;             PG8_WAIT_L(8); PG8_BAR; PG8_WAIT_L(0); PG8_MMA(0, 0, At, B0); PG8_BAR; PG8_SCHED;
;             PG8_LDB(B1, 1, 1); PG8_STAGE(PG8_SB(1, 0), b3, voffB);
;             PG8_BAR; PG8_WAIT_L(0); PG8_MMA(0, 1, At, B1); PG8_BAR;
;             PG8_LDA(At, 1, 1); PG8_STAGE(PG8_SA(1, 0), a3, voffA);
	s_add_u32 s56, s44, 0x80000
	s_addc_u32 s57, s45, 0
	s_add_i32 s55, s48, s10
	v_lshl_add_u64 v[144:145], s[56:57], 0, v[132:133]
	s_mov_b32 m0, s55
	s_nop 0
	global_load_lds_dwordx4 v[144:145], off
	v_lshl_add_u64 v[144:145], s[56:57], 0, v[128:129]
	s_add_i32 m0, s55, 0x2000
	s_nop 0
	global_load_lds_dwordx4 v[144:145], off
	s_waitcnt vmcnt(6)
	s_barrier
	s_setprio 1
	v_mfma_f32_16x16x32_bf16 v[52:55], v[204:207], v[172:175], v[52:55]
	v_mfma_f32_16x16x32_bf16 v[48:51], v[212:215], v[172:175], v[48:51]
	v_mfma_f32_16x16x32_bf16 v[36:39], v[204:207], v[180:183], v[36:39]
	v_mfma_f32_16x16x32_bf16 v[32:35], v[212:215], v[180:183], v[32:35]
	v_mfma_f32_16x16x32_bf16 v[20:23], v[204:207], v[188:191], v[20:23]
	v_mfma_f32_16x16x32_bf16 v[16:19], v[212:215], v[188:191], v[16:19]
	v_mfma_f32_16x16x32_bf16 v[4:7], v[204:207], v[196:199], v[4:7]
	v_mfma_f32_16x16x32_bf16 v[0:3], v[212:215], v[196:199], v[0:3]
	v_mfma_f32_16x16x32_bf16 v[52:55], v[208:211], v[176:179], v[52:55]
	v_mfma_f32_16x16x32_bf16 v[48:51], v[216:219], v[176:179], v[48:51]
	v_mfma_f32_16x16x32_bf16 v[36:39], v[208:211], v[184:187], v[36:39]
	v_mfma_f32_16x16x32_bf16 v[32:35], v[216:219], v[184:187], v[32:35]
	v_mfma_f32_16x16x32_bf16 v[20:23], v[208:211], v[192:195], v[20:23]
	v_mfma_f32_16x16x32_bf16 v[16:19], v[216:219], v[192:195], v[16:19]
	v_mfma_f32_16x16x32_bf16 v[4:7], v[208:211], v[200:203], v[4:7]
	v_mfma_f32_16x16x32_bf16 v[0:3], v[216:219], v[200:203], v[0:3]
	s_setprio 0
	s_add_i32 s55, 0, 0x18000
	v_add_u32_e32 v168, s55, v151
	s_barrier
	ds_read_b128 v[144:147], v168
	ds_read_b128 v[160:163], v168 offset:1024
	ds_read_b128 v[164:167], v168 offset:2048
	ds_read_b128 v[168:171], v168 offset:3072
	s_add_u32 s46, s46, 0x80000
	s_addc_u32 s47, s47, 0
	s_mov_b32 m0, s30
	v_lshl_add_u64 v[204:205], s[46:47], 0, v[134:135]
	ds_read_b128 v[172:175], v154 offset:32768
	ds_read_b128 v[176:179], v154 offset:33792
	ds_read_b128 v[180:183], v154 offset:34816
	ds_read_b128 v[184:187], v154 offset:35840
	ds_read_b128 v[188:191], v154 offset:36864
	ds_read_b128 v[192:195], v154 offset:37888
	ds_read_b128 v[196:199], v154 offset:38912
	ds_read_b128 v[200:203], v154 offset:39936
	global_load_lds_dwordx4 v[204:205], off
	v_lshl_add_u64 v[204:205], s[46:47], 0, v[130:131]
	s_mov_b32 m0, s31
	s_nop 0
	global_load_lds_dwordx4 v[204:205], off
	s_waitcnt lgkmcnt(8)
	s_barrier
	s_waitcnt lgkmcnt(0)
	s_setprio 1
	s_waitcnt lgkmcnt(0)
	v_mfma_f32_16x16x32_bf16 v[124:127], v[144:147], v[172:175], v[124:127]
	v_mfma_f32_16x16x32_bf16 v[120:123], v[164:167], v[172:175], v[120:123]
	v_mfma_f32_16x16x32_bf16 v[108:111], v[144:147], v[180:183], v[108:111]
	v_mfma_f32_16x16x32_bf16 v[104:107], v[164:167], v[180:183], v[104:107]
	v_mfma_f32_16x16x32_bf16 v[92:95], v[144:147], v[188:191], v[92:95]
	v_mfma_f32_16x16x32_bf16 v[88:91], v[164:167], v[188:191], v[88:91]
	v_mfma_f32_16x16x32_bf16 v[76:79], v[144:147], v[196:199], v[76:79]
	v_mfma_f32_16x16x32_bf16 v[72:75], v[164:167], v[196:199], v[72:75]
	v_mfma_f32_16x16x32_bf16 v[124:127], v[160:163], v[176:179], v[124:127]
	v_mfma_f32_16x16x32_bf16 v[120:123], v[168:171], v[176:179], v[120:123]
	v_mfma_f32_16x16x32_bf16 v[108:111], v[160:163], v[184:187], v[108:111]
	v_mfma_f32_16x16x32_bf16 v[104:107], v[168:171], v[184:187], v[104:107]
	v_mfma_f32_16x16x32_bf16 v[92:95], v[160:163], v[192:195], v[92:95]
	v_mfma_f32_16x16x32_bf16 v[88:91], v[168:171], v[192:195], v[88:91]
	v_mfma_f32_16x16x32_bf16 v[76:79], v[160:163], v[200:203], v[76:79]
	v_mfma_f32_16x16x32_bf16 v[72:75], v[168:171], v[200:203], v[72:75]
	s_setprio 0
	s_barrier
	s_add_i32 s46, 0, 0x1c000
	s_add_i32 s47, s55, s10
	v_add_u32_e32 v216, s46, v151
	v_lshl_add_u64 v[148:149], v[148:149], 0, s[8:9]
	s_mov_b32 m0, s47
	ds_read_b128 v[204:207], v216
	ds_read_b128 v[208:211], v216 offset:1024
	ds_read_b128 v[212:215], v216 offset:2048
	ds_read_b128 v[216:219], v216 offset:3072
	global_load_lds_dwordx4 v[148:149], off
	v_lshl_add_u64 v[148:149], v[156:157], 0, s[8:9]
	s_add_i32 m0, s47, 0x2000
	s_nop 0
	global_load_lds_dwordx4 v[148:149], off
	s_barrier
	s_waitcnt lgkmcnt(0)
	s_setprio 1
	s_waitcnt lgkmcnt(0)
	v_mfma_f32_16x16x32_bf16 v[116:119], v[204:207], v[172:175], v[116:119]
	v_mfma_f32_16x16x32_bf16 v[112:115], v[212:215], v[172:175], v[112:115]
	v_mfma_f32_16x16x32_bf16 v[100:103], v[204:207], v[180:183], v[100:103]
	v_mfma_f32_16x16x32_bf16 v[96:99], v[212:215], v[180:183], v[96:99]
	v_mfma_f32_16x16x32_bf16 v[84:87], v[204:207], v[188:191], v[84:87]
	v_mfma_f32_16x16x32_bf16 v[80:83], v[212:215], v[188:191], v[80:83]
	v_mfma_f32_16x16x32_bf16 v[68:71], v[204:207], v[196:199], v[68:71]
	v_mfma_f32_16x16x32_bf16 v[64:67], v[212:215], v[196:199], v[64:67]
	v_mfma_f32_16x16x32_bf16 v[116:119], v[208:211], v[176:179], v[116:119]
	v_mfma_f32_16x16x32_bf16 v[112:115], v[216:219], v[176:179], v[112:115]
	v_mfma_f32_16x16x32_bf16 v[100:103], v[208:211], v[184:187], v[100:103]
	v_mfma_f32_16x16x32_bf16 v[96:99], v[216:219], v[184:187], v[96:99]
	v_mfma_f32_16x16x32_bf16 v[84:87], v[208:211], v[192:195], v[84:87]
	v_mfma_f32_16x16x32_bf16 v[80:83], v[216:219], v[192:195], v[80:83]
	v_mfma_f32_16x16x32_bf16 v[68:71], v[208:211], v[200:203], v[68:71]
	v_mfma_f32_16x16x32_bf16 v[64:67], v[216:219], v[200:203], v[64:67]
	s_setprio 0
	s_mov_b32 m0, s36
	v_lshl_add_u64 v[148:149], v[220:221], 0, s[8:9]
	s_barrier
	ds_read_b128 v[172:175], v154 offset:49152
	ds_read_b128 v[176:179], v154 offset:50176
	ds_read_b128 v[180:183], v154 offset:51200
	ds_read_b128 v[184:187], v154 offset:52224
	ds_read_b128 v[188:191], v154 offset:53248
	ds_read_b128 v[192:195], v154 offset:54272
	ds_read_b128 v[196:199], v154 offset:55296
	ds_read_b128 v[200:203], v154 offset:56320
	global_load_lds_dwordx4 v[148:149], off
	v_lshl_add_u64 v[148:149], v[222:223], 0, s[8:9]
	s_mov_b32 m0, s37
	s_nop 0
	global_load_lds_dwordx4 v[148:149], off
	s_barrier
; __device__ __forceinline__ float fast_rcp(float x) { return __builtin_amdgcn_rcpf(x); }
; __device__ __forceinline__ float fast_exp2(float x) { return __builtin_amdgcn_exp2f(x); }
; #define PG8_STAGE(bufoff, gbase, voff) do { _Pragma("unroll") for (int _i = 0; _i < 2; ++_i) \
;         __builtin_amdgcn_global_load_lds((const unsigned*)((const char*)(gbase) + (voff)[_i]), (LAS unsigned*)(lds + (bufoff) + ldsw + _i * 8192), 16, 0, 0); } while (0)
; #define PG8_MMA(ai, bj, At, Bt) do { __builtin_amdgcn_s_setprio(1); _Pragma("unroll") for (int m = 0; m < 4; ++m) _Pragma("unroll") for (int n = 0; n < 2; ++n) _Pragma("unroll") for (int k = 0; k < 2; ++k) \
;         acc[ai][bj][m][n] = __builtin_amdgcn_mfma_f32_16x16x32_bf16(Bt[n][k], At[m][k], acc[ai][bj][m][n], 0, 0, 0); __builtin_amdgcn_s_setprio(0); } while (0)
; #define PG8_WAIT_V(n) asm volatile("s_waitcnt vmcnt(" #n ")" ::: "memory")
; #define PG8_WAIT_L(n) asm volatile("s_waitcnt lgkmcnt(" #n ")" ::: "memory")
; #define PG8_BAR __builtin_amdgcn_s_barrier()
; #define PG8_SCHED __builtin_amdgcn_sched_barrier(0)
; template <class Epi>
; __device__ __forceinline__ void gemm_phase(LAS unsigned char* lds, const Gemm g, const StaticOrder& S, const Epi& E) {
;     ...
;             PG8_BAR; PG8_WAIT_L(0); PG8_MMA(1, 0, At, B0); PG8_BAR; PG8_SCHED;
;             PG8_STAGE(PG8_SB(1, 1), b3 + hstep, voffB);
;             PG8_WAIT_V(6); PG8_BAR; PG8_MMA(1, 1, At, B1); PG8_BAR;
;     __device__ __forceinline__ void operator()(const f32x4 (&acc)[2][2][4][2], const Unit& u, int wr, int wc, int fr, int fq) const {
;         const int row0 = u.pm * BM + wr * 64 + fr, col0 = u.pn * HALF + wc * 32 + 8 * fq;
; #pragma unroll
;         for (int ai = 0; ai < 2; ++ai)
; #pragma unroll
;             for (int m = 0; m < 4; ++m) { bf16_t* rowp = O + (size_t)(row0 + ai * HALF + m * 16) * DFF + col0;
;                 const float r = rs[row0 + ai * HALF + m * 16], r2 = r * r;
;                 f32x4 h0, h1;
; #pragma unroll
;                 for (int j = 0; j < 4; ++j) {
;                     const float g0 = acc[ai][0][m][0][j], g1 = acc[ai][0][m][1][j];
;                     h0[j] = g0 * r2 * fast_rcp(1.0f + fast_exp2(g0 * (-LOG2E * r))) * acc[ai][1][m][0][j];
;                     h1[j] = g1 * r2 * fast_rcp(1.0f + fast_exp2(g1 * (-LOG2E * r))) * acc[ai][1][m][1][j]; }
;                 *(u32x4*)rowp = pack8(h0, h1); }
	s_waitcnt lgkmcnt(0)
	s_setprio 1
	s_waitcnt lgkmcnt(0)
	v_mfma_f32_16x16x32_bf16 v[60:63], v[144:147], v[172:175], v[60:63]
	v_mfma_f32_16x16x32_bf16 v[56:59], v[164:167], v[172:175], v[56:59]
	v_mfma_f32_16x16x32_bf16 v[44:47], v[144:147], v[180:183], v[44:47]
	v_mfma_f32_16x16x32_bf16 v[40:43], v[164:167], v[180:183], v[40:43]
	v_mfma_f32_16x16x32_bf16 v[28:31], v[144:147], v[188:191], v[28:31]
	v_mfma_f32_16x16x32_bf16 v[24:27], v[164:167], v[188:191], v[24:27]
	v_mfma_f32_16x16x32_bf16 v[12:15], v[144:147], v[196:199], v[12:15]
	v_mfma_f32_16x16x32_bf16 v[8:11], v[164:167], v[196:199], v[8:11]
	v_mfma_f32_16x16x32_bf16 v[60:63], v[160:163], v[176:179], v[60:63]
	v_mfma_f32_16x16x32_bf16 v[56:59], v[168:171], v[176:179], v[56:59]
	v_mfma_f32_16x16x32_bf16 v[44:47], v[160:163], v[184:187], v[44:47]
	v_mfma_f32_16x16x32_bf16 v[40:43], v[168:171], v[184:187], v[40:43]
	v_mfma_f32_16x16x32_bf16 v[28:31], v[160:163], v[192:195], v[28:31]
	v_mfma_f32_16x16x32_bf16 v[24:27], v[168:171], v[192:195], v[24:27]
	v_mfma_f32_16x16x32_bf16 v[12:15], v[160:163], v[200:203], v[12:15]
	v_mfma_f32_16x16x32_bf16 v[8:11], v[168:171], v[200:203], v[8:11]
	s_setprio 0
	s_barrier
	s_add_u32 s44, s44, 0x80080
	s_addc_u32 s45, s45, 0
	s_add_i32 s46, s46, s10
	v_lshl_add_u64 v[144:145], s[44:45], 0, v[132:133]
	s_mov_b32 m0, s46
	s_nop 0
	global_load_lds_dwordx4 v[144:145], off
	v_lshl_add_u64 v[144:145], s[44:45], 0, v[128:129]
	s_add_i32 m0, s46, 0x2000
	s_nop 0
	global_load_lds_dwordx4 v[144:145], off
	s_waitcnt vmcnt(6)
	s_barrier
	s_setprio 1
	v_mfma_f32_16x16x32_bf16 v[52:55], v[204:207], v[172:175], v[52:55]
	v_mfma_f32_16x16x32_bf16 v[48:51], v[212:215], v[172:175], v[48:51]
	v_mfma_f32_16x16x32_bf16 v[36:39], v[204:207], v[180:183], v[36:39]
	v_mfma_f32_16x16x32_bf16 v[32:35], v[212:215], v[180:183], v[32:35]
	v_mfma_f32_16x16x32_bf16 v[20:23], v[204:207], v[188:191], v[20:23]
	v_mfma_f32_16x16x32_bf16 v[16:19], v[212:215], v[188:191], v[16:19]
	v_mfma_f32_16x16x32_bf16 v[4:7], v[204:207], v[196:199], v[4:7]
	v_mfma_f32_16x16x32_bf16 v[0:3], v[212:215], v[196:199], v[0:3]
	v_mfma_f32_16x16x32_bf16 v[52:55], v[208:211], v[176:179], v[52:55]
	v_mfma_f32_16x16x32_bf16 v[48:51], v[216:219], v[176:179], v[48:51]
	v_mfma_f32_16x16x32_bf16 v[36:39], v[208:211], v[184:187], v[36:39]
	v_mfma_f32_16x16x32_bf16 v[32:35], v[216:219], v[184:187], v[32:35]
	v_mfma_f32_16x16x32_bf16 v[20:23], v[208:211], v[192:195], v[20:23]
	v_mfma_f32_16x16x32_bf16 v[16:19], v[216:219], v[192:195], v[16:19]
	v_mfma_f32_16x16x32_bf16 v[4:7], v[208:211], v[200:203], v[4:7]
	v_mfma_f32_16x16x32_bf16 v[0:3], v[216:219], v[200:203], v[0:3]
	s_setprio 0
	s_add_i32 s54, s54, 2
	s_add_u32 s42, s42, 0x100
	s_addc_u32 s43, s43, 0
	s_add_u32 s52, s52, 0x100
	s_addc_u32 s53, s53, 0
	s_cmp_gt_u32 s54, 29
	s_barrier
	s_cbranch_scc0 .LBB0_203
	v_lshl_add_u32 v144, s40, 8, v150
	v_ashrrev_i32_e32 v145, 31, v144
	v_lshl_add_u64 v[148:149], v[144:145], 2, s[14:15]
	global_load_dword v145, v[148:149], off
	global_load_dword v204, v[148:149], off offset:64
	global_load_dword v205, v[148:149], off offset:128
	global_load_dword v206, v[148:149], off offset:192
	global_load_dword v207, v[148:149], off offset:512
	global_load_dword v208, v[148:149], off offset:576
	global_load_dword v209, v[148:149], off offset:640
	global_load_dword v210, v[148:149], off offset:704
	v_lshl_or_b32 v156, s34, 7, v152
	v_ashrrev_i32_e32 v157, 31, v156
	v_mov_b64_e32 v[146:147], s[20:21]
	v_mad_i64_i32 v[160:161], s[42:43], v144, s49, v[146:147]
	s_and_b64 vcc, exec, s[4:5]
	s_mov_b32 s34, s22
	s_mov_b32 s40, s24
	s_mov_b64 s[44:45], s[28:29]
	s_waitcnt vmcnt(0)
	v_mul_f32_e32 v162, v145, v145
	v_mul_f32_e32 v145, 0xbfb8aa3b, v145
	v_mul_f32_e32 v163, v124, v162
	v_mul_f32_e32 v124, v124, v145
	v_exp_f32_e32 v124, v124
	s_nop 0
	v_add_f32_e32 v124, 1.0, v124
	v_rcp_f32_e32 v124, v124
	s_nop 0
	v_mul_f32_e32 v124, v163, v124
	v_mul_f32_e32 v116, v116, v124
	v_mul_f32_e32 v124, v120, v162
	v_mul_f32_e32 v120, v120, v145
	v_exp_f32_e32 v120, v120
	s_nop 0
	v_add_f32_e32 v120, 1.0, v120
	v_rcp_f32_e32 v120, v120
	s_nop 0
	v_mul_f32_e32 v120, v124, v120
	v_mul_f32_e32 v124, v125, v145
	v_exp_f32_e32 v124, v124
	v_mul_f32_e32 v120, v112, v120
	v_mul_f32_e32 v112, v125, v162
	v_add_f32_e32 v124, 1.0, v124
	v_rcp_f32_e32 v124, v124
	s_nop 0
	v_mul_f32_e32 v112, v112, v124
	v_mul_f32_e32 v117, v117, v112
	v_mul_f32_e32 v112, v121, v162
	v_mul_f32_e32 v121, v121, v145
	v_exp_f32_e32 v121, v121
	s_nop 0
	v_add_f32_e32 v121, 1.0, v121
	v_rcp_f32_e32 v121, v121
	s_nop 0
	v_mul_f32_e32 v112, v112, v121
	v_mul_f32_e32 v121, v113, v112
	v_mul_f32_e32 v113, v126, v145
	v_exp_f32_e32 v113, v113
	v_mul_f32_e32 v112, v126, v162
	v_add_f32_e32 v113, 1.0, v113
	v_rcp_f32_e32 v113, v113
	s_nop 0
	v_mul_f32_e32 v112, v112, v113
	v_mul_f32_e32 v113, v122, v145
	v_exp_f32_e32 v113, v113
	v_mul_f32_e32 v124, v118, v112
	v_mul_f32_e32 v112, v122, v162
	v_add_f32_e32 v113, 1.0, v113
	v_rcp_f32_e32 v113, v113
	s_nop 0
	v_mul_f32_e32 v112, v112, v113
	v_mul_f32_e32 v113, v127, v145
	v_exp_f32_e32 v113, v113
	v_mul_f32_e32 v122, v114, v112
	v_mul_f32_e32 v112, v127, v162
	v_cvt_pk_bf16_f32 v114, v116, v117
	v_add_f32_e32 v113, 1.0, v113
	v_rcp_f32_e32 v113, v113
	s_nop 0
	v_mul_f32_e32 v112, v112, v113
	v_mul_f32_e32 v113, v123, v145
	v_exp_f32_e32 v113, v113
	v_mul_f32_e32 v125, v119, v112
	v_mul_f32_e32 v112, v123, v162
	v_add_f32_e32 v113, 1.0, v113
	v_rcp_f32_e32 v113, v113
	s_nop 0
	v_mul_f32_e32 v112, v112, v113
	v_mul_f32_e32 v123, v115, v112
	v_lshlrev_b64 v[112:113], 1, v[156:157]
	v_lshl_add_u64 v[118:119], v[160:161], 0, v[112:113]
; __device__ __forceinline__ float fast_rcp(float x) { return __builtin_amdgcn_rcpf(x); }
; __device__ __forceinline__ float fast_exp2(float x) { return __builtin_amdgcn_exp2f(x); }
; __device__ __forceinline__ u32x4 pack8(f32x4 v0, f32x4 v1) { u32x4 w; w.x = cvt_pk_bf16(v0[0], v0[1]); w.y = cvt_pk_bf16(v0[2], v0[3]); w.z = cvt_pk_bf16(v1[0], v1[1]); w.w = cvt_pk_bf16(v1[2], v1[3]); return w; }
;     __device__ __forceinline__ void operator()(const f32x4 (&acc)[2][2][4][2], const Unit& u, int wr, int wc, int fr, int fq) const {
;     ...
;         for (int ai = 0; ai < 2; ++ai)
; #pragma unroll
;             for (int m = 0; m < 4; ++m) { bf16_t* rowp = O + (size_t)(row0 + ai * HALF + m * 16) * DFF + col0;
;                 const float r = rs[row0 + ai * HALF + m * 16], r2 = r * r;
;                 f32x4 h0, h1;
; #pragma unroll
;                 for (int j = 0; j < 4; ++j) {
;                     const float g0 = acc[ai][0][m][0][j], g1 = acc[ai][0][m][1][j];
;                     h0[j] = g0 * r2 * fast_rcp(1.0f + fast_exp2(g0 * (-LOG2E * r))) * acc[ai][1][m][0][j];
;                     h1[j] = g1 * r2 * fast_rcp(1.0f + fast_exp2(g1 * (-LOG2E * r))) * acc[ai][1][m][1][j]; }
;                 *(u32x4*)rowp = pack8(h0, h1); }
	v_cvt_pk_bf16_f32 v115, v124, v125
	v_cvt_pk_bf16_f32 v116, v120, v121
	v_cvt_pk_bf16_f32 v117, v122, v123
	global_store_dwordx4 v[118:119], v[114:117], off
	s_nop 1
	v_mov_b32_e32 v116, v204
	s_nop 0
	v_or_b32_e32 v114, 16, v144
	v_mad_i64_i32 v[114:115], s[42:43], v114, s49, v[146:147]
	v_mul_f32_e32 v117, v116, v116
	v_mul_f32_e32 v116, 0xbfb8aa3b, v116
	v_mul_f32_e32 v118, v108, v117
	v_mul_f32_e32 v108, v108, v116
	v_exp_f32_e32 v108, v108
	s_nop 0
	v_add_f32_e32 v108, 1.0, v108
	v_rcp_f32_e32 v108, v108
	s_nop 0
	v_mul_f32_e32 v108, v118, v108
	v_mul_f32_e32 v108, v100, v108
	v_mul_f32_e32 v100, v104, v117
	v_mul_f32_e32 v104, v104, v116
	v_exp_f32_e32 v104, v104
	s_nop 0
	v_add_f32_e32 v104, 1.0, v104
	v_rcp_f32_e32 v104, v104
	s_nop 0
	v_mul_f32_e32 v100, v100, v104
	v_mul_f32_e32 v104, v96, v100
	v_mul_f32_e32 v100, v109, v116
	v_exp_f32_e32 v100, v100
	v_mul_f32_e32 v96, v109, v117
	v_add_f32_e32 v100, 1.0, v100
	v_rcp_f32_e32 v100, v100
	s_nop 0
	v_mul_f32_e32 v96, v96, v100
	v_mul_f32_e32 v96, v101, v96
	v_mul_f32_e32 v101, v105, v116
	v_exp_f32_e32 v101, v101
	v_mul_f32_e32 v100, v105, v117
	v_cvt_pk_bf16_f32 v96, v108, v96
	v_add_f32_e32 v101, 1.0, v101
	v_rcp_f32_e32 v101, v101
	s_nop 0
	v_mul_f32_e32 v100, v100, v101
	v_mul_f32_e32 v105, v97, v100
	v_mul_f32_e32 v100, v110, v116
	v_exp_f32_e32 v100, v100
	v_mul_f32_e32 v101, v106, v116
	v_exp_f32_e32 v101, v101
	v_mul_f32_e32 v97, v110, v117
	v_add_f32_e32 v100, 1.0, v100
	v_rcp_f32_e32 v100, v100
	v_add_f32_e32 v101, 1.0, v101
	v_rcp_f32_e32 v101, v101
	v_mul_f32_e32 v97, v97, v100
	v_mul_f32_e32 v100, v106, v117
	v_mul_f32_e32 v100, v100, v101
	v_mul_f32_e32 v97, v102, v97
	v_mul_f32_e32 v102, v98, v100
	v_mul_f32_e32 v100, v111, v116
	v_exp_f32_e32 v100, v100
	v_mul_f32_e32 v101, v107, v116
	v_exp_f32_e32 v101, v101
	v_mul_f32_e32 v98, v111, v117
	v_add_f32_e32 v100, 1.0, v100
	v_rcp_f32_e32 v100, v100
	v_add_f32_e32 v101, 1.0, v101
	v_rcp_f32_e32 v101, v101
	v_mul_f32_e32 v98, v98, v100
	v_mul_f32_e32 v100, v107, v117
	v_mul_f32_e32 v100, v100, v101
	v_mul_f32_e32 v98, v103, v98
	v_mul_f32_e32 v99, v99, v100
	v_lshl_add_u64 v[100:101], v[114:115], 0, v[112:113]
	v_cvt_pk_bf16_f32 v97, v97, v98
	v_cvt_pk_bf16_f32 v98, v104, v105
	v_cvt_pk_bf16_f32 v99, v102, v99
	global_store_dwordx4 v[100:101], v[96:99], off
	s_nop 1
	v_mov_b32_e32 v98, v205
	s_nop 0
	v_or_b32_e32 v96, 32, v144
	v_mad_i64_i32 v[96:97], s[42:43], v96, s49, v[146:147]
	v_mul_f32_e32 v99, v98, v98
	v_mul_f32_e32 v98, 0xbfb8aa3b, v98
	v_mul_f32_e32 v100, v92, v99
	v_mul_f32_e32 v92, v92, v98
	v_exp_f32_e32 v92, v92
	s_nop 0
	v_add_f32_e32 v92, 1.0, v92
	v_rcp_f32_e32 v92, v92
	s_nop 0
	v_mul_f32_e32 v92, v100, v92
	v_mul_f32_e32 v92, v84, v92
	v_mul_f32_e32 v84, v88, v99
	v_mul_f32_e32 v88, v88, v98
	v_exp_f32_e32 v88, v88
	s_nop 0
	v_add_f32_e32 v88, 1.0, v88
	v_rcp_f32_e32 v88, v88
	s_nop 0
	v_mul_f32_e32 v84, v84, v88
	v_mul_f32_e32 v88, v80, v84
	v_mul_f32_e32 v84, v93, v98
	v_exp_f32_e32 v84, v84
	v_mul_f32_e32 v80, v93, v99
	v_add_f32_e32 v84, 1.0, v84
	v_rcp_f32_e32 v84, v84
	s_nop 0
	v_mul_f32_e32 v80, v80, v84
	v_mul_f32_e32 v80, v85, v80
	v_mul_f32_e32 v85, v89, v98
	v_exp_f32_e32 v85, v85
	v_mul_f32_e32 v84, v89, v99
	v_cvt_pk_bf16_f32 v80, v92, v80
	v_add_f32_e32 v85, 1.0, v85
	v_rcp_f32_e32 v85, v85
	s_nop 0
	v_mul_f32_e32 v84, v84, v85
	v_mul_f32_e32 v89, v81, v84
	v_mul_f32_e32 v84, v94, v98
	v_exp_f32_e32 v84, v84
	v_mul_f32_e32 v85, v90, v98
	v_exp_f32_e32 v85, v85
	v_mul_f32_e32 v81, v94, v99
	v_add_f32_e32 v84, 1.0, v84
	v_rcp_f32_e32 v84, v84
	v_add_f32_e32 v85, 1.0, v85
	v_rcp_f32_e32 v85, v85
	v_mul_f32_e32 v81, v81, v84
	v_mul_f32_e32 v84, v90, v99
	v_mul_f32_e32 v84, v84, v85
	v_mul_f32_e32 v81, v86, v81
	v_mul_f32_e32 v86, v82, v84
	v_mul_f32_e32 v84, v95, v98
	v_exp_f32_e32 v84, v84
	v_mul_f32_e32 v85, v91, v98
	v_exp_f32_e32 v85, v85
	v_mul_f32_e32 v82, v95, v99
	v_add_f32_e32 v84, 1.0, v84
	v_rcp_f32_e32 v84, v84
	v_add_f32_e32 v85, 1.0, v85
	v_rcp_f32_e32 v85, v85
	v_mul_f32_e32 v82, v82, v84
	v_mul_f32_e32 v84, v91, v99
	v_mul_f32_e32 v84, v84, v85
	v_mul_f32_e32 v82, v87, v82
	v_mul_f32_e32 v83, v83, v84
	v_lshl_add_u64 v[84:85], v[96:97], 0, v[112:113]
	v_cvt_pk_bf16_f32 v81, v81, v82
	v_cvt_pk_bf16_f32 v82, v88, v89
	v_cvt_pk_bf16_f32 v83, v86, v83
	global_store_dwordx4 v[84:85], v[80:83], off
	s_nop 1
	v_mov_b32_e32 v82, v206
	s_nop 0
	v_or_b32_e32 v80, 48, v144
	v_mad_i64_i32 v[80:81], s[42:43], v80, s49, v[146:147]
	v_mul_f32_e32 v83, v82, v82
	v_mul_f32_e32 v82, 0xbfb8aa3b, v82
	v_mul_f32_e32 v84, v76, v83
	v_mul_f32_e32 v76, v76, v82
	v_exp_f32_e32 v76, v76
	s_nop 0
	v_add_f32_e32 v76, 1.0, v76
	v_rcp_f32_e32 v76, v76
	s_nop 0
	v_mul_f32_e32 v76, v84, v76
	v_mul_f32_e32 v76, v68, v76
	v_mul_f32_e32 v68, v72, v83
	v_mul_f32_e32 v72, v72, v82
	v_exp_f32_e32 v72, v72
	s_nop 0
	v_add_f32_e32 v72, 1.0, v72
	v_rcp_f32_e32 v72, v72
	s_nop 0
	v_mul_f32_e32 v68, v68, v72
	v_mul_f32_e32 v72, v64, v68
	v_mul_f32_e32 v68, v77, v82
	v_exp_f32_e32 v68, v68
	v_mul_f32_e32 v64, v77, v83
	v_add_f32_e32 v68, 1.0, v68
	v_rcp_f32_e32 v68, v68
	s_nop 0
	v_mul_f32_e32 v64, v64, v68
	v_mul_f32_e32 v64, v69, v64
	v_mul_f32_e32 v69, v73, v82
	v_exp_f32_e32 v69, v69
	v_mul_f32_e32 v68, v73, v83
	v_cvt_pk_bf16_f32 v64, v76, v64
	v_add_f32_e32 v69, 1.0, v69
	v_rcp_f32_e32 v69, v69
	s_nop 0
	v_mul_f32_e32 v68, v68, v69
	v_mul_f32_e32 v73, v65, v68
	v_mul_f32_e32 v68, v78, v82
	v_exp_f32_e32 v68, v68
	v_mul_f32_e32 v69, v74, v82
	v_exp_f32_e32 v69, v69
	v_mul_f32_e32 v65, v78, v83
	v_add_f32_e32 v68, 1.0, v68
	v_rcp_f32_e32 v68, v68
	v_add_f32_e32 v69, 1.0, v69
	v_rcp_f32_e32 v69, v69
; __device__ __forceinline__ float fast_rcp(float x) { return __builtin_amdgcn_rcpf(x); }
; __device__ __forceinline__ float fast_exp2(float x) { return __builtin_amdgcn_exp2f(x); }
; __device__ __forceinline__ u32x4 pack8(f32x4 v0, f32x4 v1) { u32x4 w; w.x = cvt_pk_bf16(v0[0], v0[1]); w.y = cvt_pk_bf16(v0[2], v0[3]); w.z = cvt_pk_bf16(v1[0], v1[1]); w.w = cvt_pk_bf16(v1[2], v1[3]); return w; }
;     __device__ __forceinline__ void operator()(const f32x4 (&acc)[2][2][4][2], const Unit& u, int wr, int wc, int fr, int fq) const {
;     ...
;         for (int ai = 0; ai < 2; ++ai)
; #pragma unroll
;             for (int m = 0; m < 4; ++m) { bf16_t* rowp = O + (size_t)(row0 + ai * HALF + m * 16) * DFF + col0;
;                 const float r = rs[row0 + ai * HALF + m * 16], r2 = r * r;
;                 f32x4 h0, h1;
; #pragma unroll
;                 for (int j = 0; j < 4; ++j) {
;                     const float g0 = acc[ai][0][m][0][j], g1 = acc[ai][0][m][1][j];
;                     h0[j] = g0 * r2 * fast_rcp(1.0f + fast_exp2(g0 * (-LOG2E * r))) * acc[ai][1][m][0][j];
;                     h1[j] = g1 * r2 * fast_rcp(1.0f + fast_exp2(g1 * (-LOG2E * r))) * acc[ai][1][m][1][j]; }
;                 *(u32x4*)rowp = pack8(h0, h1); }
	v_mul_f32_e32 v65, v65, v68
	v_mul_f32_e32 v68, v74, v83
	v_mul_f32_e32 v68, v68, v69
	v_mul_f32_e32 v65, v70, v65
	v_mul_f32_e32 v70, v66, v68
	v_mul_f32_e32 v68, v79, v82
	v_exp_f32_e32 v68, v68
	v_mul_f32_e32 v69, v75, v82
	v_exp_f32_e32 v69, v69
	v_mul_f32_e32 v66, v79, v83
	v_add_f32_e32 v68, 1.0, v68
	v_rcp_f32_e32 v68, v68
	v_add_f32_e32 v69, 1.0, v69
	v_rcp_f32_e32 v69, v69
	v_mul_f32_e32 v66, v66, v68
	v_mul_f32_e32 v68, v75, v83
	v_mul_f32_e32 v68, v68, v69
	v_mul_f32_e32 v66, v71, v66
	v_mul_f32_e32 v67, v67, v68
	v_lshl_add_u64 v[68:69], v[80:81], 0, v[112:113]
	v_cvt_pk_bf16_f32 v65, v65, v66
	v_cvt_pk_bf16_f32 v66, v72, v73
	v_cvt_pk_bf16_f32 v67, v70, v67
	global_store_dwordx4 v[68:69], v[64:67], off
	s_nop 1
	v_mov_b32_e32 v66, v207
	s_nop 0
	v_add_u32_e32 v64, 0x80, v144
	v_mad_i64_i32 v[64:65], s[42:43], v64, s49, v[146:147]
	v_mul_f32_e32 v67, v66, v66
	v_mul_f32_e32 v66, 0xbfb8aa3b, v66
	v_mul_f32_e32 v68, v60, v67
	v_mul_f32_e32 v60, v60, v66
	v_exp_f32_e32 v60, v60
	s_nop 0
	v_add_f32_e32 v60, 1.0, v60
	v_rcp_f32_e32 v60, v60
	s_nop 0
	v_mul_f32_e32 v60, v68, v60
	v_mul_f32_e32 v60, v52, v60
	v_mul_f32_e32 v52, v56, v67
	v_mul_f32_e32 v56, v56, v66
	v_exp_f32_e32 v56, v56
	s_nop 0
	v_add_f32_e32 v56, 1.0, v56
	v_rcp_f32_e32 v56, v56
	s_nop 0
	v_mul_f32_e32 v52, v52, v56
	v_mul_f32_e32 v56, v48, v52
	v_mul_f32_e32 v52, v61, v66
	v_exp_f32_e32 v52, v52
	v_mul_f32_e32 v48, v61, v67
	v_add_f32_e32 v52, 1.0, v52
	v_rcp_f32_e32 v52, v52
	s_nop 0
	v_mul_f32_e32 v48, v48, v52
	v_mul_f32_e32 v48, v53, v48
	v_mul_f32_e32 v53, v57, v66
	v_exp_f32_e32 v53, v53
	v_mul_f32_e32 v52, v57, v67
	v_cvt_pk_bf16_f32 v48, v60, v48
	v_add_f32_e32 v53, 1.0, v53
	v_rcp_f32_e32 v53, v53
	s_nop 0
	v_mul_f32_e32 v52, v52, v53
	v_mul_f32_e32 v57, v49, v52
	v_mul_f32_e32 v52, v62, v66
	v_exp_f32_e32 v52, v52
	v_mul_f32_e32 v53, v58, v66
	v_exp_f32_e32 v53, v53
	v_mul_f32_e32 v49, v62, v67
	v_add_f32_e32 v52, 1.0, v52
	v_rcp_f32_e32 v52, v52
	v_add_f32_e32 v53, 1.0, v53
	v_rcp_f32_e32 v53, v53
	v_mul_f32_e32 v49, v49, v52
	v_mul_f32_e32 v52, v58, v67
	v_mul_f32_e32 v52, v52, v53
	v_mul_f32_e32 v49, v54, v49
	v_mul_f32_e32 v54, v50, v52
	v_mul_f32_e32 v52, v63, v66
	v_exp_f32_e32 v52, v52
	v_mul_f32_e32 v53, v59, v66
	v_exp_f32_e32 v53, v53
	v_mul_f32_e32 v50, v63, v67
	v_add_f32_e32 v52, 1.0, v52
	v_rcp_f32_e32 v52, v52
	v_add_f32_e32 v53, 1.0, v53
	v_rcp_f32_e32 v53, v53
	v_mul_f32_e32 v50, v50, v52
	v_mul_f32_e32 v52, v59, v67
	v_mul_f32_e32 v52, v52, v53
	v_mul_f32_e32 v50, v55, v50
	v_mul_f32_e32 v51, v51, v52
	v_lshl_add_u64 v[52:53], v[64:65], 0, v[112:113]
	v_cvt_pk_bf16_f32 v49, v49, v50
	v_cvt_pk_bf16_f32 v50, v56, v57
	v_cvt_pk_bf16_f32 v51, v54, v51
	global_store_dwordx4 v[52:53], v[48:51], off
	s_nop 1
	v_mov_b32_e32 v50, v208
	s_nop 0
	v_add_u32_e32 v48, 0x90, v144
	v_mad_i64_i32 v[48:49], s[42:43], v48, s49, v[146:147]
	v_mul_f32_e32 v51, v50, v50
	v_mul_f32_e32 v50, 0xbfb8aa3b, v50
	v_mul_f32_e32 v52, v44, v51
	v_mul_f32_e32 v44, v44, v50
	v_exp_f32_e32 v44, v44
	s_nop 0
	v_add_f32_e32 v44, 1.0, v44
	v_rcp_f32_e32 v44, v44
	s_nop 0
	v_mul_f32_e32 v44, v52, v44
	v_mul_f32_e32 v44, v36, v44
	v_mul_f32_e32 v36, v40, v51
	v_mul_f32_e32 v40, v40, v50
	v_exp_f32_e32 v40, v40
	s_nop 0
	v_add_f32_e32 v40, 1.0, v40
	v_rcp_f32_e32 v40, v40
	s_nop 0
	v_mul_f32_e32 v36, v36, v40
	v_mul_f32_e32 v40, v32, v36
	v_mul_f32_e32 v36, v45, v50
	v_exp_f32_e32 v36, v36
	v_mul_f32_e32 v32, v45, v51
	v_add_f32_e32 v36, 1.0, v36
	v_rcp_f32_e32 v36, v36
	s_nop 0
	v_mul_f32_e32 v32, v32, v36
	v_mul_f32_e32 v32, v37, v32
	v_mul_f32_e32 v37, v41, v50
	v_exp_f32_e32 v37, v37
	v_mul_f32_e32 v36, v41, v51
	v_cvt_pk_bf16_f32 v32, v44, v32
	v_add_f32_e32 v37, 1.0, v37
	v_rcp_f32_e32 v37, v37
	s_nop 0
	v_mul_f32_e32 v36, v36, v37
	v_mul_f32_e32 v41, v33, v36
	v_mul_f32_e32 v36, v46, v50
	v_exp_f32_e32 v36, v36
	v_mul_f32_e32 v37, v42, v50
	v_exp_f32_e32 v37, v37
	v_mul_f32_e32 v33, v46, v51
	v_add_f32_e32 v36, 1.0, v36
	v_rcp_f32_e32 v36, v36
	v_add_f32_e32 v37, 1.0, v37
	v_rcp_f32_e32 v37, v37
	v_mul_f32_e32 v33, v33, v36
	v_mul_f32_e32 v36, v42, v51
	v_mul_f32_e32 v36, v36, v37
	v_mul_f32_e32 v33, v38, v33
	v_mul_f32_e32 v38, v34, v36
	v_mul_f32_e32 v36, v47, v50
	v_exp_f32_e32 v36, v36
	v_mul_f32_e32 v37, v43, v50
	v_exp_f32_e32 v37, v37
	v_mul_f32_e32 v34, v47, v51
	v_add_f32_e32 v36, 1.0, v36
	v_rcp_f32_e32 v36, v36
	v_add_f32_e32 v37, 1.0, v37
; __device__ __forceinline__ float fast_rcp(float x) { return __builtin_amdgcn_rcpf(x); }
; __device__ __forceinline__ float fast_exp2(float x) { return __builtin_amdgcn_exp2f(x); }
; #define PG8_WAIT_V(n) asm volatile("s_waitcnt vmcnt(" #n ")" ::: "memory")
; #define PG8_BAR __builtin_amdgcn_s_barrier()
; __device__ __forceinline__ u32x4 pack8(f32x4 v0, f32x4 v1) { u32x4 w; w.x = cvt_pk_bf16(v0[0], v0[1]); w.y = cvt_pk_bf16(v0[2], v0[3]); w.z = cvt_pk_bf16(v1[0], v1[1]); w.w = cvt_pk_bf16(v1[2], v1[3]); return w; }
; template <class Epi>
; __device__ __forceinline__ void gemm_phase(LAS unsigned char* lds, const Gemm g, const StaticOrder& S, const Epi& E) {
;     ...
;         if (!has_next) break;
; #pragma unroll
;         for (int a = 0; a < 2; ++a)
; #pragma unroll
;             for (int b = 0; b < 2; ++b)
; #pragma unroll
;                 for (int m = 0; m < 4; ++m)
; #pragma unroll
;                     for (int n = 0; n < 2; ++n) acc[a][b][m][n] = (f32x4){0.f, 0.f, 0.f, 0.f};
;         cur = nxt; cA = nA; cB = nB; ++ui;
;     }
;     PG8_WAIT_V(0);
;     if (wr == 0) PG8_BAR;
;     PG8_BAR;
;     __device__ __forceinline__ void operator()(const f32x4 (&acc)[2][2][4][2], const Unit& u, int wr, int wc, int fr, int fq) const {
;     ...
;         for (int ai = 0; ai < 2; ++ai)
; #pragma unroll
;             for (int m = 0; m < 4; ++m) { bf16_t* rowp = O + (size_t)(row0 + ai * HALF + m * 16) * DFF + col0;
;                 const float r = rs[row0 + ai * HALF + m * 16], r2 = r * r;
;                 f32x4 h0, h1;
; #pragma unroll
;                 for (int j = 0; j < 4; ++j) {
;                     const float g0 = acc[ai][0][m][0][j], g1 = acc[ai][0][m][1][j];
;                     h0[j] = g0 * r2 * fast_rcp(1.0f + fast_exp2(g0 * (-LOG2E * r))) * acc[ai][1][m][0][j];
;                     h1[j] = g1 * r2 * fast_rcp(1.0f + fast_exp2(g1 * (-LOG2E * r))) * acc[ai][1][m][1][j]; }
;                 *(u32x4*)rowp = pack8(h0, h1); }
	v_rcp_f32_e32 v37, v37
	v_mul_f32_e32 v34, v34, v36
	v_mul_f32_e32 v36, v43, v51
	v_mul_f32_e32 v36, v36, v37
	v_mul_f32_e32 v34, v39, v34
	v_mul_f32_e32 v35, v35, v36
	v_lshl_add_u64 v[36:37], v[48:49], 0, v[112:113]
	v_cvt_pk_bf16_f32 v33, v33, v34
	v_cvt_pk_bf16_f32 v34, v40, v41
	v_cvt_pk_bf16_f32 v35, v38, v35
	global_store_dwordx4 v[36:37], v[32:35], off
	s_nop 1
	v_mov_b32_e32 v34, v209
	s_nop 0
	v_add_u32_e32 v32, 0xa0, v144
	v_mad_i64_i32 v[32:33], s[42:43], v32, s49, v[146:147]
	v_mul_f32_e32 v35, v34, v34
	v_mul_f32_e32 v34, 0xbfb8aa3b, v34
	v_mul_f32_e32 v36, v28, v35
	v_mul_f32_e32 v28, v28, v34
	v_exp_f32_e32 v28, v28
	s_nop 0
	v_add_f32_e32 v28, 1.0, v28
	v_rcp_f32_e32 v28, v28
	s_nop 0
	v_mul_f32_e32 v28, v36, v28
	v_mul_f32_e32 v28, v20, v28
	v_mul_f32_e32 v20, v24, v35
	v_mul_f32_e32 v24, v24, v34
	v_exp_f32_e32 v24, v24
	s_nop 0
	v_add_f32_e32 v24, 1.0, v24
	v_rcp_f32_e32 v24, v24
	s_nop 0
	v_mul_f32_e32 v20, v20, v24
	v_mul_f32_e32 v24, v16, v20
	v_mul_f32_e32 v20, v29, v34
	v_exp_f32_e32 v20, v20
	v_mul_f32_e32 v16, v29, v35
	v_add_f32_e32 v20, 1.0, v20
	v_rcp_f32_e32 v20, v20
	s_nop 0
	v_mul_f32_e32 v16, v16, v20
	v_mul_f32_e32 v16, v21, v16
	v_mul_f32_e32 v21, v25, v34
	v_exp_f32_e32 v21, v21
	v_mul_f32_e32 v20, v25, v35
	v_cvt_pk_bf16_f32 v16, v28, v16
	v_add_f32_e32 v21, 1.0, v21
	v_rcp_f32_e32 v21, v21
	s_nop 0
	v_mul_f32_e32 v20, v20, v21
	v_mul_f32_e32 v25, v17, v20
	v_mul_f32_e32 v20, v30, v34
	v_exp_f32_e32 v20, v20
	v_mul_f32_e32 v21, v26, v34
	v_exp_f32_e32 v21, v21
	v_mul_f32_e32 v17, v30, v35
	v_add_f32_e32 v20, 1.0, v20
	v_rcp_f32_e32 v20, v20
	v_add_f32_e32 v21, 1.0, v21
	v_rcp_f32_e32 v21, v21
	v_mul_f32_e32 v17, v17, v20
	v_mul_f32_e32 v20, v26, v35
	v_mul_f32_e32 v20, v20, v21
	v_mul_f32_e32 v17, v22, v17
	v_mul_f32_e32 v22, v18, v20
	v_mul_f32_e32 v20, v31, v34
	v_exp_f32_e32 v20, v20
	v_mul_f32_e32 v21, v27, v34
	v_exp_f32_e32 v21, v21
	v_mul_f32_e32 v18, v31, v35
	v_add_f32_e32 v20, 1.0, v20
	v_rcp_f32_e32 v20, v20
	v_add_f32_e32 v21, 1.0, v21
	v_rcp_f32_e32 v21, v21
	v_mul_f32_e32 v18, v18, v20
	v_mul_f32_e32 v20, v27, v35
	v_mul_f32_e32 v20, v20, v21
	v_mul_f32_e32 v18, v23, v18
	v_mul_f32_e32 v19, v19, v20
	v_lshl_add_u64 v[20:21], v[32:33], 0, v[112:113]
	v_cvt_pk_bf16_f32 v17, v17, v18
	v_cvt_pk_bf16_f32 v18, v24, v25
	v_cvt_pk_bf16_f32 v19, v22, v19
	global_store_dwordx4 v[20:21], v[16:19], off
	s_nop 1
	v_mov_b32_e32 v18, v210
	s_nop 0
	v_add_u32_e32 v16, 0xb0, v144
	v_mad_i64_i32 v[16:17], s[42:43], v16, s49, v[146:147]
	s_mov_b64 s[42:43], s[26:27]
	v_mul_f32_e32 v19, v18, v18
	v_mul_f32_e32 v18, 0xbfb8aa3b, v18
	v_mul_f32_e32 v20, v12, v19
	v_mul_f32_e32 v12, v12, v18
	v_exp_f32_e32 v12, v12
	s_nop 0
	v_add_f32_e32 v12, 1.0, v12
	v_rcp_f32_e32 v12, v12
	s_nop 0
	v_mul_f32_e32 v12, v20, v12
	v_mul_f32_e32 v12, v4, v12
	v_mul_f32_e32 v4, v8, v19
	v_mul_f32_e32 v8, v8, v18
	v_exp_f32_e32 v8, v8
	s_nop 0
	v_add_f32_e32 v8, 1.0, v8
	v_rcp_f32_e32 v8, v8
	s_nop 0
	v_mul_f32_e32 v4, v4, v8
	v_mul_f32_e32 v8, v0, v4
	v_mul_f32_e32 v4, v13, v18
	v_exp_f32_e32 v4, v4
	v_mul_f32_e32 v0, v13, v19
	v_add_f32_e32 v4, 1.0, v4
	v_rcp_f32_e32 v4, v4
	s_nop 0
	v_mul_f32_e32 v0, v0, v4
	v_mul_f32_e32 v0, v5, v0
	v_mul_f32_e32 v5, v9, v18
	v_exp_f32_e32 v5, v5
	v_mul_f32_e32 v4, v9, v19
	v_cvt_pk_bf16_f32 v0, v12, v0
	v_add_f32_e32 v5, 1.0, v5
	v_rcp_f32_e32 v5, v5
	s_nop 0
	v_mul_f32_e32 v4, v4, v5
	v_mul_f32_e32 v9, v1, v4
	v_mul_f32_e32 v4, v14, v18
	v_exp_f32_e32 v4, v4
	v_mul_f32_e32 v5, v10, v18
	v_exp_f32_e32 v5, v5
	v_mul_f32_e32 v1, v14, v19
	v_add_f32_e32 v4, 1.0, v4
	v_rcp_f32_e32 v4, v4
	v_add_f32_e32 v5, 1.0, v5
	v_rcp_f32_e32 v5, v5
	v_mul_f32_e32 v1, v1, v4
	v_mul_f32_e32 v4, v10, v19
	v_mul_f32_e32 v4, v4, v5
	v_mul_f32_e32 v1, v6, v1
	v_mul_f32_e32 v6, v2, v4
	v_mul_f32_e32 v4, v15, v18
	v_exp_f32_e32 v4, v4
	v_mul_f32_e32 v5, v11, v18
	v_exp_f32_e32 v5, v5
	v_mul_f32_e32 v2, v15, v19
	v_add_f32_e32 v4, 1.0, v4
	v_rcp_f32_e32 v4, v4
	v_add_f32_e32 v5, 1.0, v5
	v_rcp_f32_e32 v5, v5
	v_mul_f32_e32 v2, v2, v4
	v_mul_f32_e32 v4, v11, v19
	v_mul_f32_e32 v4, v4, v5
	v_mul_f32_e32 v2, v7, v2
	v_mul_f32_e32 v3, v3, v4
	v_lshl_add_u64 v[4:5], v[16:17], 0, v[112:113]
	v_cvt_pk_bf16_f32 v1, v1, v2
	v_cvt_pk_bf16_f32 v2, v8, v9
	v_cvt_pk_bf16_f32 v3, v6, v3
	global_store_dwordx4 v[4:5], v[0:3], off
	s_cbranch_vccz .LBB0_200
	s_waitcnt vmcnt(0)
	s_cmpk_gt_u32 s3, 0xff
	s_cbranch_scc1 .LBB0_207
	s_barrier

; #define PG8_STAGE(bufoff, gbase, voff) do { _Pragma("unroll") for (int _i = 0; _i < 2; ++_i) \
;         __builtin_amdgcn_global_load_lds((const unsigned*)((const char*)(gbase) + (voff)[_i]), (LAS unsigned*)(lds + (bufoff) + ldsw + _i * 8192), 16, 0, 0); } while (0)
; #define PG8_LDA(dst, b, h) do { _Pragma("unroll") for (int m = 0; m < 4; ++m) _Pragma("unroll") for (int k = 0; k < 2; ++k) dst[m][k] = *(const LAS bf16x8*)(lds + PG8_SA(b, h) + aoff + m * 2048 + k * 1024); } while (0)
; #define PG8_LDB(dst, b, h) do { _Pragma("unroll") for (int n = 0; n < 2; ++n) _Pragma("unroll") for (int k = 0; k < 2; ++k) dst[n][k] = *(const LAS bf16x8*)(lds + PG8_SB(b, h) + boff + n * 2048 + k * 1024); } while (0)
; #define PG8_MMA(ai, bj, At, Bt) do { __builtin_amdgcn_s_setprio(1); _Pragma("unroll") for (int m = 0; m < 4; ++m) _Pragma("unroll") for (int n = 0; n < 2; ++n) _Pragma("unroll") for (int k = 0; k < 2; ++k) \
;         acc[ai][bj][m][n] = __builtin_amdgcn_mfma_f32_16x16x32_bf16(Bt[n][k], At[m][k], acc[ai][bj][m][n], 0, 0, 0); __builtin_amdgcn_s_setprio(0); } while (0)
; #define PG8_WAIT_L(n) asm volatile("s_waitcnt lgkmcnt(" #n ")" ::: "memory")
; #define PG8_BAR __builtin_amdgcn_s_barrier()
; #define PG8_SCHED __builtin_amdgcn_sched_barrier(0)
; template <class Epi>
; __device__ __forceinline__ void gemm_phase(LAS unsigned char* lds, const Gemm g, const StaticOrder& S, const Epi& E) {
;     ...
;             PG8_LDB(B0, 0, 0); PG8_SCHED; PG8_LDA(At, 0, 0); PG8_STAGE(PG8_SA(1, 1), a1 + hstep, voffA);
;             PG8_WAIT_L(8); PG8_BAR; PG8_WAIT_L(0); PG8_MMA(0, 0, At, B0); PG8_BAR; PG8_SCHED;
;             PG8_LDB(B1, 0, 1); PG8_STAGE(PG8_SB(0, 0), b2, voffB);
;             PG8_BAR; PG8_WAIT_L(0); PG8_MMA(0, 1, At, B1); PG8_BAR;
;             PG8_LDA(At, 0, 1); PG8_STAGE(PG8_SA(0, 0), a2, voffA);
;             PG8_BAR; PG8_WAIT_L(0); PG8_MMA(1, 0, At, B0); PG8_BAR; PG8_SCHED;
.LBB0_407:
	ds_read_b128 v[150:153], v164
	ds_read_b128 v[154:157], v164 offset:1024
	ds_read_b128 v[168:171], v164 offset:2048
	ds_read_b128 v[172:175], v164 offset:3072
	s_add_u32 s48, s46, 0xfff80080
	s_addc_u32 s49, s47, -1
	s_cmp_eq_u32 s57, 28
	s_cselect_b32 s51, s9, s49
	s_cselect_b32 s50, s45, s48
	s_cselect_b32 s49, s7, s56
	s_cselect_b32 s48, s54, s55
	v_lshl_add_u64 v[208:209], s[46:47], 0, v[142:143]
	s_add_i32 m0, s27, 0xc000
	ds_read_b128 v[176:179], v165
	ds_read_b128 v[180:183], v165 offset:1024
	ds_read_b128 v[184:187], v165 offset:2048
	ds_read_b128 v[188:191], v165 offset:3072
	ds_read_b128 v[192:195], v165 offset:4096
	ds_read_b128 v[196:199], v165 offset:5120
	ds_read_b128 v[200:203], v165 offset:6144
	ds_read_b128 v[204:207], v165 offset:7168
	global_load_lds_dwordx4 v[208:209], off
	v_lshl_add_u64 v[208:209], s[46:47], 0, v[144:145]
	s_add_i32 m0, s27, 0xe000
	s_nop 0
	global_load_lds_dwordx4 v[208:209], off
	s_waitcnt lgkmcnt(8)
	s_barrier
	s_waitcnt lgkmcnt(0)
	s_setprio 1
	s_waitcnt lgkmcnt(0)
	v_mfma_f32_16x16x32_bf16 v[124:127], v[150:153], v[176:179], v[124:127]
	v_mfma_f32_16x16x32_bf16 v[120:123], v[168:171], v[176:179], v[120:123]
	v_mfma_f32_16x16x32_bf16 v[108:111], v[150:153], v[184:187], v[108:111]
	v_mfma_f32_16x16x32_bf16 v[104:107], v[168:171], v[184:187], v[104:107]
	v_mfma_f32_16x16x32_bf16 v[92:95], v[150:153], v[192:195], v[92:95]
	v_mfma_f32_16x16x32_bf16 v[88:91], v[168:171], v[192:195], v[88:91]
	v_mfma_f32_16x16x32_bf16 v[76:79], v[150:153], v[200:203], v[76:79]
	v_mfma_f32_16x16x32_bf16 v[72:75], v[168:171], v[200:203], v[72:75]
	v_mfma_f32_16x16x32_bf16 v[124:127], v[154:157], v[180:183], v[124:127]
	v_mfma_f32_16x16x32_bf16 v[120:123], v[172:175], v[180:183], v[120:123]
	v_mfma_f32_16x16x32_bf16 v[108:111], v[154:157], v[188:191], v[108:111]
	v_mfma_f32_16x16x32_bf16 v[104:107], v[172:175], v[188:191], v[104:107]
	v_mfma_f32_16x16x32_bf16 v[92:95], v[154:157], v[196:199], v[92:95]
	v_mfma_f32_16x16x32_bf16 v[88:91], v[172:175], v[196:199], v[88:91]
	v_mfma_f32_16x16x32_bf16 v[76:79], v[154:157], v[204:207], v[76:79]
	v_mfma_f32_16x16x32_bf16 v[72:75], v[172:175], v[204:207], v[72:75]
	s_setprio 0
	s_barrier
	s_add_i32 s58, s41, s23
	v_lshl_add_u64 v[224:225], s[48:49], 0, v[132:133]
	s_mov_b32 m0, s58
	ds_read_b128 v[208:211], v166
	ds_read_b128 v[212:215], v166 offset:1024
	ds_read_b128 v[216:219], v166 offset:2048
	ds_read_b128 v[220:223], v166 offset:3072
	global_load_lds_dwordx4 v[224:225], off
	v_lshl_add_u64 v[226:227], s[48:49], 0, v[128:129]
	s_add_i32 m0, s58, 0x2000
	s_nop 0
	global_load_lds_dwordx4 v[226:227], off
	s_barrier
	s_waitcnt lgkmcnt(0)
	s_setprio 1
	s_waitcnt lgkmcnt(0)
	v_mfma_f32_16x16x32_bf16 v[116:119], v[208:211], v[176:179], v[116:119]
	v_mfma_f32_16x16x32_bf16 v[112:115], v[216:219], v[176:179], v[112:115]
	v_mfma_f32_16x16x32_bf16 v[100:103], v[208:211], v[184:187], v[100:103]
	v_mfma_f32_16x16x32_bf16 v[96:99], v[216:219], v[184:187], v[96:99]
	v_mfma_f32_16x16x32_bf16 v[84:87], v[208:211], v[192:195], v[84:87]
	v_mfma_f32_16x16x32_bf16 v[80:83], v[216:219], v[192:195], v[80:83]
	v_mfma_f32_16x16x32_bf16 v[68:71], v[208:211], v[200:203], v[68:71]
	v_mfma_f32_16x16x32_bf16 v[64:67], v[216:219], v[200:203], v[64:67]
	v_mfma_f32_16x16x32_bf16 v[116:119], v[212:215], v[180:183], v[116:119]
	v_mfma_f32_16x16x32_bf16 v[112:115], v[220:223], v[180:183], v[112:115]
	v_mfma_f32_16x16x32_bf16 v[100:103], v[212:215], v[188:191], v[100:103]
	v_mfma_f32_16x16x32_bf16 v[96:99], v[220:223], v[188:191], v[96:99]
	v_mfma_f32_16x16x32_bf16 v[84:87], v[212:215], v[196:199], v[84:87]
	v_mfma_f32_16x16x32_bf16 v[80:83], v[220:223], v[196:199], v[80:83]
	v_mfma_f32_16x16x32_bf16 v[68:71], v[212:215], v[204:207], v[68:71]
	v_mfma_f32_16x16x32_bf16 v[64:67], v[220:223], v[204:207], v[64:67]
	s_setprio 0
	s_mov_b32 m0, s27
	v_lshl_add_u64 v[228:229], s[50:51], 0, v[134:135]
	s_barrier
	ds_read_b128 v[176:179], v165 offset:16384
	ds_read_b128 v[180:183], v165 offset:17408
	ds_read_b128 v[184:187], v165 offset:18432
	ds_read_b128 v[188:191], v165 offset:19456
	ds_read_b128 v[192:195], v165 offset:20480
	ds_read_b128 v[196:199], v165 offset:21504
	ds_read_b128 v[200:203], v165 offset:22528
	ds_read_b128 v[204:207], v165 offset:23552
	global_load_lds_dwordx4 v[228:229], off
	v_lshl_add_u64 v[230:231], s[50:51], 0, v[130:131]
	s_mov_b32 m0, s30
	s_nop 0
	global_load_lds_dwordx4 v[230:231], off
	s_barrier
	s_waitcnt lgkmcnt(0)
	s_setprio 1
	s_waitcnt lgkmcnt(0)
	v_mfma_f32_16x16x32_bf16 v[60:63], v[150:153], v[176:179], v[60:63]
	v_mfma_f32_16x16x32_bf16 v[56:59], v[168:171], v[176:179], v[56:59]
	v_mfma_f32_16x16x32_bf16 v[44:47], v[150:153], v[184:187], v[44:47]
	v_mfma_f32_16x16x32_bf16 v[40:43], v[168:171], v[184:187], v[40:43]
	v_mfma_f32_16x16x32_bf16 v[28:31], v[150:153], v[192:195], v[28:31]
	v_mfma_f32_16x16x32_bf16 v[24:27], v[168:171], v[192:195], v[24:27]
	v_mfma_f32_16x16x32_bf16 v[12:15], v[150:153], v[200:203], v[12:15]
	v_mfma_f32_16x16x32_bf16 v[8:11], v[168:171], v[200:203], v[8:11]
	v_mfma_f32_16x16x32_bf16 v[60:63], v[154:157], v[180:183], v[60:63]
	v_mfma_f32_16x16x32_bf16 v[56:59], v[172:175], v[180:183], v[56:59]
	v_mfma_f32_16x16x32_bf16 v[44:47], v[154:157], v[188:191], v[44:47]
	v_mfma_f32_16x16x32_bf16 v[40:43], v[172:175], v[188:191], v[40:43]
	v_mfma_f32_16x16x32_bf16 v[28:31], v[154:157], v[196:199], v[28:31]
	v_mfma_f32_16x16x32_bf16 v[24:27], v[172:175], v[196:199], v[24:27]
	v_mfma_f32_16x16x32_bf16 v[12:15], v[154:157], v[204:207], v[12:15]
	v_mfma_f32_16x16x32_bf16 v[8:11], v[172:175], v[204:207], v[8:11]
	s_setprio 0
	s_barrier
; #define PG8_STAGE(bufoff, gbase, voff) do { _Pragma("unroll") for (int _i = 0; _i < 2; ++_i) \
;         __builtin_amdgcn_global_load_lds((const unsigned*)((const char*)(gbase) + (voff)[_i]), (LAS unsigned*)(lds + (bufoff) + ldsw + _i * 8192), 16, 0, 0); } while (0)
; #define PG8_LDA(dst, b, h) do { _Pragma("unroll") for (int m = 0; m < 4; ++m) _Pragma("unroll") for (int k = 0; k < 2; ++k) dst[m][k] = *(const LAS bf16x8*)(lds + PG8_SA(b, h) + aoff + m * 2048 + k * 1024); } while (0)
; #define PG8_LDB(dst, b, h) do { _Pragma("unroll") for (int n = 0; n < 2; ++n) _Pragma("unroll") for (int k = 0; k < 2; ++k) dst[n][k] = *(const LAS bf16x8*)(lds + PG8_SB(b, h) + boff + n * 2048 + k * 1024); } while (0)
; #define PG8_MMA(ai, bj, At, Bt) do { __builtin_amdgcn_s_setprio(1); _Pragma("unroll") for (int m = 0; m < 4; ++m) _Pragma("unroll") for (int n = 0; n < 2; ++n) _Pragma("unroll") for (int k = 0; k < 2; ++k) \
;         acc[ai][bj][m][n] = __builtin_amdgcn_mfma_f32_16x16x32_bf16(Bt[n][k], At[m][k], acc[ai][bj][m][n], 0, 0, 0); __builtin_amdgcn_s_setprio(0); } while (0)
; #define PG8_WAIT_V(n) asm volatile("s_waitcnt vmcnt(" #n ")" ::: "memory")
; #define PG8_WAIT_L(n) asm volatile("s_waitcnt lgkmcnt(" #n ")" ::: "memory")
; #define PG8_BAR __builtin_amdgcn_s_barrier()
; #define PG8_SCHED __builtin_amdgcn_sched_barrier(0)
; template <class Epi>
; __device__ __forceinline__ void gemm_phase(LAS unsigned char* lds, const Gemm g, const StaticOrder& S, const Epi& E) {
;     ...
;             PG8_STAGE(PG8_SB(0, 1), b2 + hstep, voffB);
;             PG8_WAIT_V(6); PG8_BAR; PG8_MMA(1, 1, At, B1); PG8_BAR;
;             PG8_LDB(B0, 1, 0); PG8_SCHED; PG8_LDA(At, 1, 0); PG8_STAGE(PG8_SA(0, 1), a2 + hstep, voffA);
;             PG8_WAIT_L(8); PG8_BAR; PG8_WAIT_L(0); PG8_MMA(0, 0, At, B0); PG8_BAR; PG8_SCHED;
;             PG8_LDB(B1, 1, 1); PG8_STAGE(PG8_SB(1, 0), b3, voffB);
;             PG8_BAR; PG8_WAIT_L(0); PG8_MMA(0, 1, At, B1); PG8_BAR;
;             PG8_LDA(At, 1, 1); PG8_STAGE(PG8_SA(1, 0), a3, voffA);
	s_add_u32 s58, s48, 0x80000
	s_addc_u32 s59, s49, 0
	s_add_i32 s60, s52, s23
	v_lshl_add_u64 v[150:151], s[58:59], 0, v[132:133]
	s_mov_b32 m0, s60
	s_nop 0
	global_load_lds_dwordx4 v[150:151], off
	v_lshl_add_u64 v[150:151], s[58:59], 0, v[128:129]
	s_add_i32 m0, s60, 0x2000
	s_nop 0
	global_load_lds_dwordx4 v[150:151], off
	s_waitcnt vmcnt(6)
	s_barrier
	s_setprio 1
	v_mfma_f32_16x16x32_bf16 v[52:55], v[208:211], v[176:179], v[52:55]
	v_mfma_f32_16x16x32_bf16 v[48:51], v[216:219], v[176:179], v[48:51]
	v_mfma_f32_16x16x32_bf16 v[36:39], v[208:211], v[184:187], v[36:39]
	v_mfma_f32_16x16x32_bf16 v[32:35], v[216:219], v[184:187], v[32:35]
	v_mfma_f32_16x16x32_bf16 v[20:23], v[208:211], v[192:195], v[20:23]
	v_mfma_f32_16x16x32_bf16 v[16:19], v[216:219], v[192:195], v[16:19]
	v_mfma_f32_16x16x32_bf16 v[4:7], v[208:211], v[200:203], v[4:7]
	v_mfma_f32_16x16x32_bf16 v[0:3], v[216:219], v[200:203], v[0:3]
	v_mfma_f32_16x16x32_bf16 v[52:55], v[212:215], v[180:183], v[52:55]
	v_mfma_f32_16x16x32_bf16 v[48:51], v[220:223], v[180:183], v[48:51]
	v_mfma_f32_16x16x32_bf16 v[36:39], v[212:215], v[188:191], v[36:39]
	v_mfma_f32_16x16x32_bf16 v[32:35], v[220:223], v[188:191], v[32:35]
	v_mfma_f32_16x16x32_bf16 v[20:23], v[212:215], v[196:199], v[20:23]
	v_mfma_f32_16x16x32_bf16 v[16:19], v[220:223], v[196:199], v[16:19]
	v_mfma_f32_16x16x32_bf16 v[4:7], v[212:215], v[204:207], v[4:7]
	v_mfma_f32_16x16x32_bf16 v[0:3], v[220:223], v[204:207], v[0:3]
	s_setprio 0
	s_add_i32 s58, 0, 0x18000
	v_add_u32_e32 v136, s58, v161
	s_barrier
	ds_read_b128 v[150:153], v136
	ds_read_b128 v[154:157], v136 offset:1024
	ds_read_b128 v[168:171], v136 offset:2048
	ds_read_b128 v[172:175], v136 offset:3072
	s_add_u32 s50, s50, 0x80000
	s_addc_u32 s51, s51, 0
	s_mov_b32 m0, s31
	v_lshl_add_u64 v[208:209], s[50:51], 0, v[134:135]
	ds_read_b128 v[176:179], v165 offset:32768
	ds_read_b128 v[180:183], v165 offset:33792
	ds_read_b128 v[184:187], v165 offset:34816
	ds_read_b128 v[188:191], v165 offset:35840
	ds_read_b128 v[192:195], v165 offset:36864
	ds_read_b128 v[196:199], v165 offset:37888
	ds_read_b128 v[200:203], v165 offset:38912
	ds_read_b128 v[204:207], v165 offset:39936
	global_load_lds_dwordx4 v[208:209], off
	v_lshl_add_u64 v[208:209], s[50:51], 0, v[130:131]
	s_mov_b32 m0, s33
	s_nop 0
	global_load_lds_dwordx4 v[208:209], off
	s_waitcnt lgkmcnt(8)
	s_barrier
	s_waitcnt lgkmcnt(0)
	s_setprio 1
	s_waitcnt lgkmcnt(0)
	v_mfma_f32_16x16x32_bf16 v[124:127], v[150:153], v[176:179], v[124:127]
	v_mfma_f32_16x16x32_bf16 v[120:123], v[168:171], v[176:179], v[120:123]
	v_mfma_f32_16x16x32_bf16 v[108:111], v[150:153], v[184:187], v[108:111]
	v_mfma_f32_16x16x32_bf16 v[104:107], v[168:171], v[184:187], v[104:107]
	v_mfma_f32_16x16x32_bf16 v[92:95], v[150:153], v[192:195], v[92:95]
	v_mfma_f32_16x16x32_bf16 v[88:91], v[168:171], v[192:195], v[88:91]
	v_mfma_f32_16x16x32_bf16 v[76:79], v[150:153], v[200:203], v[76:79]
	v_mfma_f32_16x16x32_bf16 v[72:75], v[168:171], v[200:203], v[72:75]
	v_mfma_f32_16x16x32_bf16 v[124:127], v[154:157], v[180:183], v[124:127]
	v_mfma_f32_16x16x32_bf16 v[120:123], v[172:175], v[180:183], v[120:123]
	v_mfma_f32_16x16x32_bf16 v[108:111], v[154:157], v[188:191], v[108:111]
	v_mfma_f32_16x16x32_bf16 v[104:107], v[172:175], v[188:191], v[104:107]
	v_mfma_f32_16x16x32_bf16 v[92:95], v[154:157], v[196:199], v[92:95]
	v_mfma_f32_16x16x32_bf16 v[88:91], v[172:175], v[196:199], v[88:91]
	v_mfma_f32_16x16x32_bf16 v[76:79], v[154:157], v[204:207], v[76:79]
	v_mfma_f32_16x16x32_bf16 v[72:75], v[172:175], v[204:207], v[72:75]
	s_setprio 0
	s_barrier
	s_add_i32 s50, 0, 0x1c000
	s_add_i32 s51, s58, s23
	v_add_u32_e32 v136, s50, v161
	v_lshl_add_u64 v[224:225], v[224:225], 0, s[2:3]
	s_mov_b32 m0, s51
	ds_read_b128 v[208:211], v136
	ds_read_b128 v[212:215], v136 offset:1024
	ds_read_b128 v[216:219], v136 offset:2048
	ds_read_b128 v[220:223], v136 offset:3072
	global_load_lds_dwordx4 v[224:225], off
	v_lshl_add_u64 v[224:225], v[226:227], 0, s[2:3]
	s_add_i32 m0, s51, 0x2000
	s_nop 0
	global_load_lds_dwordx4 v[224:225], off
	s_barrier
	s_waitcnt lgkmcnt(0)
	s_setprio 1
	s_waitcnt lgkmcnt(0)
	v_mfma_f32_16x16x32_bf16 v[116:119], v[208:211], v[176:179], v[116:119]
	v_mfma_f32_16x16x32_bf16 v[112:115], v[216:219], v[176:179], v[112:115]
	v_mfma_f32_16x16x32_bf16 v[100:103], v[208:211], v[184:187], v[100:103]
	v_mfma_f32_16x16x32_bf16 v[96:99], v[216:219], v[184:187], v[96:99]
	v_mfma_f32_16x16x32_bf16 v[84:87], v[208:211], v[192:195], v[84:87]
	v_mfma_f32_16x16x32_bf16 v[80:83], v[216:219], v[192:195], v[80:83]
	v_mfma_f32_16x16x32_bf16 v[68:71], v[208:211], v[200:203], v[68:71]
	v_mfma_f32_16x16x32_bf16 v[64:67], v[216:219], v[200:203], v[64:67]
	v_mfma_f32_16x16x32_bf16 v[116:119], v[212:215], v[180:183], v[116:119]
	v_mfma_f32_16x16x32_bf16 v[112:115], v[220:223], v[180:183], v[112:115]
	v_mfma_f32_16x16x32_bf16 v[100:103], v[212:215], v[188:191], v[100:103]
	v_mfma_f32_16x16x32_bf16 v[96:99], v[220:223], v[188:191], v[96:99]
	v_mfma_f32_16x16x32_bf16 v[84:87], v[212:215], v[196:199], v[84:87]
	v_mfma_f32_16x16x32_bf16 v[80:83], v[220:223], v[196:199], v[80:83]
	v_mfma_f32_16x16x32_bf16 v[68:71], v[212:215], v[204:207], v[68:71]
	v_mfma_f32_16x16x32_bf16 v[64:67], v[220:223], v[204:207], v[64:67]
	s_setprio 0
	s_mov_b32 m0, s37
	v_lshl_add_u64 v[224:225], v[228:229], 0, s[2:3]
	s_barrier
	ds_read_b128 v[176:179], v165 offset:49152
	ds_read_b128 v[180:183], v165 offset:50176
	ds_read_b128 v[184:187], v165 offset:51200
	ds_read_b128 v[188:191], v165 offset:52224
	ds_read_b128 v[192:195], v165 offset:53248
	ds_read_b128 v[196:199], v165 offset:54272
	ds_read_b128 v[200:203], v165 offset:55296
	ds_read_b128 v[204:207], v165 offset:56320
	global_load_lds_dwordx4 v[224:225], off
	v_lshl_add_u64 v[224:225], v[230:231], 0, s[2:3]
	s_mov_b32 m0, s38
	s_nop 0
	global_load_lds_dwordx4 v[224:225], off
	s_barrier
; #define PG8_STAGE(bufoff, gbase, voff) do { _Pragma("unroll") for (int _i = 0; _i < 2; ++_i) \
;         __builtin_amdgcn_global_load_lds((const unsigned*)((const char*)(gbase) + (voff)[_i]), (LAS unsigned*)(lds + (bufoff) + ldsw + _i * 8192), 16, 0, 0); } while (0)
; #define PG8_MMA(ai, bj, At, Bt) do { __builtin_amdgcn_s_setprio(1); _Pragma("unroll") for (int m = 0; m < 4; ++m) _Pragma("unroll") for (int n = 0; n < 2; ++n) _Pragma("unroll") for (int k = 0; k < 2; ++k) \
;         acc[ai][bj][m][n] = __builtin_amdgcn_mfma_f32_16x16x32_bf16(Bt[n][k], At[m][k], acc[ai][bj][m][n], 0, 0, 0); __builtin_amdgcn_s_setprio(0); } while (0)
; #define PG8_WAIT_V(n) asm volatile("s_waitcnt vmcnt(" #n ")" ::: "memory")
; #define PG8_WAIT_L(n) asm volatile("s_waitcnt lgkmcnt(" #n ")" ::: "memory")
; #define PG8_BAR __builtin_amdgcn_s_barrier()
; #define PG8_SCHED __builtin_amdgcn_sched_barrier(0)
; __device__ __forceinline__ u32x4 pack8(f32x4 v0, f32x4 v1) { u32x4 w; w.x = cvt_pk_bf16(v0[0], v0[1]); w.y = cvt_pk_bf16(v0[2], v0[3]); w.z = cvt_pk_bf16(v1[0], v1[1]); w.w = cvt_pk_bf16(v1[2], v1[3]); return w; }
; template <class Epi>
; __device__ __forceinline__ void gemm_phase(LAS unsigned char* lds, const Gemm g, const StaticOrder& S, const Epi& E) {
;     ...
;             PG8_BAR; PG8_WAIT_L(0); PG8_MMA(1, 0, At, B0); PG8_BAR; PG8_SCHED;
;             PG8_STAGE(PG8_SB(1, 1), b3 + hstep, voffB);
;             PG8_WAIT_V(6); PG8_BAR; PG8_MMA(1, 1, At, B1); PG8_BAR;
;         }
;         E(acc, cur, wr, wc, fr, fq);
;     __device__ __forceinline__ void operator()(const f32x4 (&acc)[2][2][4][2], const Unit& u, int wr, int wc, int fr, int fq) const {
;     ...
;             const int col0 = u.pn * BM + wc * 32 + 8 * fq; const float sc = (u.pn < 2) ? QSCALE : 1.0f;
; #pragma unroll
;             for (int ai = 0; ai < 2; ++ai)
; #pragma unroll
;                 for (int m = 0; m < 4; ++m) { bf16_t* rowp = O + (size_t)(row0 + ai * HALF + m * 16) * NQKV + col0; const float scr_ = sc * rowsc[row0 + ai * HALF + m * 16];
; #pragma unroll
;                     for (int bj = 0; bj < 2; ++bj) *(u32x4*)(rowp + bj * HALF) = pack8(acc[ai][bj][m][0] * scr_, acc[ai][bj][m][1] * scr_); }
	s_waitcnt lgkmcnt(0)
	s_setprio 1
	s_waitcnt lgkmcnt(0)
	v_mfma_f32_16x16x32_bf16 v[60:63], v[150:153], v[176:179], v[60:63]
	v_mfma_f32_16x16x32_bf16 v[56:59], v[168:171], v[176:179], v[56:59]
	v_mfma_f32_16x16x32_bf16 v[44:47], v[150:153], v[184:187], v[44:47]
	v_mfma_f32_16x16x32_bf16 v[40:43], v[168:171], v[184:187], v[40:43]
	v_mfma_f32_16x16x32_bf16 v[28:31], v[150:153], v[192:195], v[28:31]
	v_mfma_f32_16x16x32_bf16 v[24:27], v[168:171], v[192:195], v[24:27]
	v_mfma_f32_16x16x32_bf16 v[12:15], v[150:153], v[200:203], v[12:15]
	v_mfma_f32_16x16x32_bf16 v[8:11], v[168:171], v[200:203], v[8:11]
	v_mfma_f32_16x16x32_bf16 v[60:63], v[154:157], v[180:183], v[60:63]
	v_mfma_f32_16x16x32_bf16 v[56:59], v[172:175], v[180:183], v[56:59]
	v_mfma_f32_16x16x32_bf16 v[44:47], v[154:157], v[188:191], v[44:47]
	v_mfma_f32_16x16x32_bf16 v[40:43], v[172:175], v[188:191], v[40:43]
	v_mfma_f32_16x16x32_bf16 v[28:31], v[154:157], v[196:199], v[28:31]
	v_mfma_f32_16x16x32_bf16 v[24:27], v[172:175], v[196:199], v[24:27]
	v_mfma_f32_16x16x32_bf16 v[12:15], v[154:157], v[204:207], v[12:15]
	v_mfma_f32_16x16x32_bf16 v[8:11], v[172:175], v[204:207], v[8:11]
	s_setprio 0
	s_barrier
	s_add_u32 s48, s48, 0x80080
	s_addc_u32 s49, s49, 0
	s_add_i32 s50, s50, s23
	v_lshl_add_u64 v[150:151], s[48:49], 0, v[132:133]
	s_mov_b32 m0, s50
	s_nop 0
	global_load_lds_dwordx4 v[150:151], off
	v_lshl_add_u64 v[150:151], s[48:49], 0, v[128:129]
	s_add_i32 m0, s50, 0x2000
	s_nop 0
	global_load_lds_dwordx4 v[150:151], off
	s_waitcnt vmcnt(6)
	s_barrier
	s_setprio 1
	v_mfma_f32_16x16x32_bf16 v[52:55], v[208:211], v[176:179], v[52:55]
	v_mfma_f32_16x16x32_bf16 v[48:51], v[216:219], v[176:179], v[48:51]
	v_mfma_f32_16x16x32_bf16 v[36:39], v[208:211], v[184:187], v[36:39]
	v_mfma_f32_16x16x32_bf16 v[32:35], v[216:219], v[184:187], v[32:35]
	v_mfma_f32_16x16x32_bf16 v[20:23], v[208:211], v[192:195], v[20:23]
	v_mfma_f32_16x16x32_bf16 v[16:19], v[216:219], v[192:195], v[16:19]
	v_mfma_f32_16x16x32_bf16 v[4:7], v[208:211], v[200:203], v[4:7]
	v_mfma_f32_16x16x32_bf16 v[0:3], v[216:219], v[200:203], v[0:3]
	v_mfma_f32_16x16x32_bf16 v[52:55], v[212:215], v[180:183], v[52:55]
	v_mfma_f32_16x16x32_bf16 v[48:51], v[220:223], v[180:183], v[48:51]
	v_mfma_f32_16x16x32_bf16 v[36:39], v[212:215], v[188:191], v[36:39]
	v_mfma_f32_16x16x32_bf16 v[32:35], v[220:223], v[188:191], v[32:35]
	v_mfma_f32_16x16x32_bf16 v[20:23], v[212:215], v[196:199], v[20:23]
	v_mfma_f32_16x16x32_bf16 v[16:19], v[220:223], v[196:199], v[16:19]
	v_mfma_f32_16x16x32_bf16 v[4:7], v[212:215], v[204:207], v[4:7]
	v_mfma_f32_16x16x32_bf16 v[0:3], v[220:223], v[204:207], v[0:3]
	s_setprio 0
	s_add_i32 s57, s57, 2
	s_add_u32 s46, s46, 0x100
	s_addc_u32 s47, s47, 0
	s_add_u32 s55, s55, 0x100
	s_addc_u32 s56, s56, 0
	s_cmp_gt_u32 s57, 29
	s_barrier
	s_cbranch_scc0 .LBB0_407
	v_lshl_add_u32 v154, s44, 8, v160
	s_add_i32 s9, s34, -6
	s_lshl_b32 s7, s34, 8
	s_cmp_gt_u32 s9, 11
	s_mov_b64 s[44:45], -1
	v_ashrrev_i32_e32 v155, 31, v154
	v_or_b32_e32 v174, 16, v154
	v_or_b32_e32 v173, 32, v154
	v_or_b32_e32 v172, 48, v154
	v_add_u32_e32 v171, 0x80, v154
	v_add_u32_e32 v170, 0x90, v154
	v_add_u32_e32 v169, 0xa0, v154
	v_add_u32_e32 v168, 0xb0, v154
	s_cbranch_scc0 .LBB0_410
	v_lshl_add_u64 v[150:151], v[154:155], 2, s[14:15]
	global_load_dword v136, v[150:151], off
	global_load_dword v204, v[150:151], off offset:64
	global_load_dword v205, v[150:151], off offset:128
	global_load_dword v206, v[150:151], off offset:192
	global_load_dword v207, v[150:151], off offset:512
	global_load_dword v208, v[150:151], off offset:576
	global_load_dword v209, v[150:151], off offset:640
	global_load_dword v210, v[150:151], off offset:704
	s_cmp_lt_i32 s34, 2
	v_or_b32_e32 v156, s7, v162
	s_cselect_b64 vcc, -1, 0
	v_mov_b64_e32 v[152:153], s[20:21]
	v_cndmask_b32_e32 v175, 1.0, v167, vcc
	v_ashrrev_i32_e32 v157, 31, v156
	v_mad_i64_i32 v[176:177], s[44:45], v154, s53, v[152:153]
	v_lshlrev_b64 v[156:157], 1, v[156:157]
	v_lshl_add_u64 v[180:181], v[176:177], 0, v[156:157]
	s_waitcnt vmcnt(0)
	v_mul_f32_e32 v136, v175, v136
	v_pk_mul_f32 v[178:179], v[126:127], v[136:137] op_sel_hi:[1,0]
	v_pk_mul_f32 v[176:177], v[124:125], v[136:137] op_sel_hi:[1,0]
	v_pk_mul_f32 v[182:183], v[122:123], v[136:137] op_sel_hi:[1,0]
	v_pk_mul_f32 v[184:185], v[120:121], v[136:137] op_sel_hi:[1,0]
	v_cvt_pk_bf16_f32 v176, v176, v177
	v_cvt_pk_bf16_f32 v177, v178, v179
	v_pk_mul_f32 v[186:187], v[118:119], v[136:137] op_sel_hi:[1,0]
	v_cvt_pk_bf16_f32 v178, v184, v185
	v_cvt_pk_bf16_f32 v179, v182, v183
	v_pk_mul_f32 v[188:189], v[116:117], v[136:137] op_sel_hi:[1,0]
	v_pk_mul_f32 v[190:191], v[114:115], v[136:137] op_sel_hi:[1,0]
	v_pk_mul_f32 v[192:193], v[112:113], v[136:137] op_sel_hi:[1,0]
	global_store_dwordx4 v[180:181], v[176:179], off
	s_nop 1
	v_cvt_pk_bf16_f32 v176, v188, v189
	v_cvt_pk_bf16_f32 v177, v186, v187
	v_cvt_pk_bf16_f32 v178, v192, v193
	v_cvt_pk_bf16_f32 v179, v190, v191
	global_store_dwordx4 v[180:181], v[176:179], off offset:256
	s_nop 1
	v_mov_b32_e32 v136, v204
	v_mul_f32_e32 v136, v175, v136
	v_mad_i64_i32 v[176:177], s[44:45], v174, s53, v[152:153]
	v_lshl_add_u64 v[180:181], v[176:177], 0, v[156:157]
	v_pk_mul_f32 v[178:179], v[110:111], v[136:137] op_sel_hi:[1,0]
	v_pk_mul_f32 v[176:177], v[108:109], v[136:137] op_sel_hi:[1,0]
	v_pk_mul_f32 v[182:183], v[106:107], v[136:137] op_sel_hi:[1,0]
	v_pk_mul_f32 v[184:185], v[104:105], v[136:137] op_sel_hi:[1,0]
	v_cvt_pk_bf16_f32 v176, v176, v177
	v_cvt_pk_bf16_f32 v177, v178, v179
	v_pk_mul_f32 v[186:187], v[102:103], v[136:137] op_sel_hi:[1,0]
	v_cvt_pk_bf16_f32 v178, v184, v185
; __device__ __forceinline__ u32x4 pack8(f32x4 v0, f32x4 v1) { u32x4 w; w.x = cvt_pk_bf16(v0[0], v0[1]); w.y = cvt_pk_bf16(v0[2], v0[3]); w.z = cvt_pk_bf16(v1[0], v1[1]); w.w = cvt_pk_bf16(v1[2], v1[3]); return w; }
;     __device__ __forceinline__ void operator()(const f32x4 (&acc)[2][2][4][2], const Unit& u, int wr, int wc, int fr, int fq) const {
;     ...
;             const int col0 = u.pn * BM + wc * 32 + 8 * fq; const float sc = (u.pn < 2) ? QSCALE : 1.0f;
; #pragma unroll
;             for (int ai = 0; ai < 2; ++ai)
; #pragma unroll
;                 for (int m = 0; m < 4; ++m) { bf16_t* rowp = O + (size_t)(row0 + ai * HALF + m * 16) * NQKV + col0; const float scr_ = sc * rowsc[row0 + ai * HALF + m * 16];
; #pragma unroll
;                     for (int bj = 0; bj < 2; ++bj) *(u32x4*)(rowp + bj * HALF) = pack8(acc[ai][bj][m][0] * scr_, acc[ai][bj][m][1] * scr_); }
	v_cvt_pk_bf16_f32 v179, v182, v183
	v_pk_mul_f32 v[188:189], v[100:101], v[136:137] op_sel_hi:[1,0]
	v_pk_mul_f32 v[190:191], v[98:99], v[136:137] op_sel_hi:[1,0]
	v_pk_mul_f32 v[192:193], v[96:97], v[136:137] op_sel_hi:[1,0]
	global_store_dwordx4 v[180:181], v[176:179], off
	s_nop 1
	v_cvt_pk_bf16_f32 v176, v188, v189
	v_cvt_pk_bf16_f32 v177, v186, v187
	v_cvt_pk_bf16_f32 v178, v192, v193
	v_cvt_pk_bf16_f32 v179, v190, v191
	global_store_dwordx4 v[180:181], v[176:179], off offset:256
	s_nop 1
	v_mov_b32_e32 v136, v205
	v_mul_f32_e32 v136, v175, v136
	v_mad_i64_i32 v[176:177], s[44:45], v173, s53, v[152:153]
	v_lshl_add_u64 v[180:181], v[176:177], 0, v[156:157]
	v_pk_mul_f32 v[178:179], v[94:95], v[136:137] op_sel_hi:[1,0]
	v_pk_mul_f32 v[176:177], v[92:93], v[136:137] op_sel_hi:[1,0]
	v_pk_mul_f32 v[182:183], v[90:91], v[136:137] op_sel_hi:[1,0]
	v_pk_mul_f32 v[184:185], v[88:89], v[136:137] op_sel_hi:[1,0]
	v_cvt_pk_bf16_f32 v176, v176, v177
	v_cvt_pk_bf16_f32 v177, v178, v179
	v_pk_mul_f32 v[186:187], v[86:87], v[136:137] op_sel_hi:[1,0]
	v_cvt_pk_bf16_f32 v178, v184, v185
	v_cvt_pk_bf16_f32 v179, v182, v183
	v_pk_mul_f32 v[188:189], v[84:85], v[136:137] op_sel_hi:[1,0]
	v_pk_mul_f32 v[190:191], v[82:83], v[136:137] op_sel_hi:[1,0]
	v_pk_mul_f32 v[192:193], v[80:81], v[136:137] op_sel_hi:[1,0]
	global_store_dwordx4 v[180:181], v[176:179], off
	s_nop 1
	v_cvt_pk_bf16_f32 v176, v188, v189
	v_cvt_pk_bf16_f32 v177, v186, v187
	v_cvt_pk_bf16_f32 v178, v192, v193
	v_cvt_pk_bf16_f32 v179, v190, v191
	global_store_dwordx4 v[180:181], v[176:179], off offset:256
	s_nop 1
	v_mov_b32_e32 v136, v206
	v_mul_f32_e32 v136, v175, v136
	v_mad_i64_i32 v[176:177], s[44:45], v172, s53, v[152:153]
	v_lshl_add_u64 v[180:181], v[176:177], 0, v[156:157]
	v_pk_mul_f32 v[178:179], v[78:79], v[136:137] op_sel_hi:[1,0]
	v_pk_mul_f32 v[176:177], v[76:77], v[136:137] op_sel_hi:[1,0]
	v_pk_mul_f32 v[182:183], v[74:75], v[136:137] op_sel_hi:[1,0]
	v_pk_mul_f32 v[184:185], v[72:73], v[136:137] op_sel_hi:[1,0]
	v_cvt_pk_bf16_f32 v176, v176, v177
	v_cvt_pk_bf16_f32 v177, v178, v179
	v_pk_mul_f32 v[186:187], v[70:71], v[136:137] op_sel_hi:[1,0]
	v_cvt_pk_bf16_f32 v178, v184, v185
	v_cvt_pk_bf16_f32 v179, v182, v183
	v_pk_mul_f32 v[188:189], v[68:69], v[136:137] op_sel_hi:[1,0]
	v_pk_mul_f32 v[190:191], v[66:67], v[136:137] op_sel_hi:[1,0]
	v_pk_mul_f32 v[192:193], v[64:65], v[136:137] op_sel_hi:[1,0]
	global_store_dwordx4 v[180:181], v[176:179], off
	s_nop 1
	v_cvt_pk_bf16_f32 v176, v188, v189
	v_cvt_pk_bf16_f32 v177, v186, v187
	v_cvt_pk_bf16_f32 v178, v192, v193
	v_cvt_pk_bf16_f32 v179, v190, v191
	global_store_dwordx4 v[180:181], v[176:179], off offset:256
	s_nop 1
	v_mov_b32_e32 v136, v207
	v_mul_f32_e32 v136, v175, v136
	v_mad_i64_i32 v[176:177], s[44:45], v171, s53, v[152:153]
	v_lshl_add_u64 v[180:181], v[176:177], 0, v[156:157]
	v_pk_mul_f32 v[178:179], v[62:63], v[136:137] op_sel_hi:[1,0]
	v_pk_mul_f32 v[176:177], v[60:61], v[136:137] op_sel_hi:[1,0]
	v_pk_mul_f32 v[182:183], v[58:59], v[136:137] op_sel_hi:[1,0]
	v_pk_mul_f32 v[184:185], v[56:57], v[136:137] op_sel_hi:[1,0]
	v_cvt_pk_bf16_f32 v176, v176, v177
	v_cvt_pk_bf16_f32 v177, v178, v179
	v_pk_mul_f32 v[186:187], v[54:55], v[136:137] op_sel_hi:[1,0]
	v_cvt_pk_bf16_f32 v178, v184, v185
	v_cvt_pk_bf16_f32 v179, v182, v183
	v_pk_mul_f32 v[188:189], v[52:53], v[136:137] op_sel_hi:[1,0]
	v_pk_mul_f32 v[190:191], v[50:51], v[136:137] op_sel_hi:[1,0]
	v_pk_mul_f32 v[192:193], v[48:49], v[136:137] op_sel_hi:[1,0]
; __device__ __forceinline__ u32x4 pack8(f32x4 v0, f32x4 v1) { u32x4 w; w.x = cvt_pk_bf16(v0[0], v0[1]); w.y = cvt_pk_bf16(v0[2], v0[3]); w.z = cvt_pk_bf16(v1[0], v1[1]); w.w = cvt_pk_bf16(v1[2], v1[3]); return w; }
;     __device__ __forceinline__ void operator()(const f32x4 (&acc)[2][2][4][2], const Unit& u, int wr, int wc, int fr, int fq) const {
;     ...
;             const int col0 = u.pn * BM + wc * 32 + 8 * fq; const float sc = (u.pn < 2) ? QSCALE : 1.0f;
; #pragma unroll
;             for (int ai = 0; ai < 2; ++ai)
; #pragma unroll
;                 for (int m = 0; m < 4; ++m) { bf16_t* rowp = O + (size_t)(row0 + ai * HALF + m * 16) * NQKV + col0; const float scr_ = sc * rowsc[row0 + ai * HALF + m * 16];
; #pragma unroll
;                     for (int bj = 0; bj < 2; ++bj) *(u32x4*)(rowp + bj * HALF) = pack8(acc[ai][bj][m][0] * scr_, acc[ai][bj][m][1] * scr_); }
	global_store_dwordx4 v[180:181], v[176:179], off
	s_nop 1
	v_cvt_pk_bf16_f32 v176, v188, v189
	v_cvt_pk_bf16_f32 v177, v186, v187
	v_cvt_pk_bf16_f32 v178, v192, v193
	v_cvt_pk_bf16_f32 v179, v190, v191
	global_store_dwordx4 v[180:181], v[176:179], off offset:256
	s_nop 1
	v_mov_b32_e32 v136, v208
	v_mul_f32_e32 v136, v175, v136
	v_mad_i64_i32 v[176:177], s[44:45], v170, s53, v[152:153]
	v_lshl_add_u64 v[180:181], v[176:177], 0, v[156:157]
	v_pk_mul_f32 v[178:179], v[46:47], v[136:137] op_sel_hi:[1,0]
	v_pk_mul_f32 v[176:177], v[44:45], v[136:137] op_sel_hi:[1,0]
	v_pk_mul_f32 v[182:183], v[42:43], v[136:137] op_sel_hi:[1,0]
	v_pk_mul_f32 v[184:185], v[40:41], v[136:137] op_sel_hi:[1,0]
	v_cvt_pk_bf16_f32 v176, v176, v177
	v_cvt_pk_bf16_f32 v177, v178, v179
	v_pk_mul_f32 v[186:187], v[38:39], v[136:137] op_sel_hi:[1,0]
	v_cvt_pk_bf16_f32 v178, v184, v185
	v_cvt_pk_bf16_f32 v179, v182, v183
	v_pk_mul_f32 v[188:189], v[36:37], v[136:137] op_sel_hi:[1,0]
	v_pk_mul_f32 v[190:191], v[34:35], v[136:137] op_sel_hi:[1,0]
	v_pk_mul_f32 v[192:193], v[32:33], v[136:137] op_sel_hi:[1,0]
	global_store_dwordx4 v[180:181], v[176:179], off
	s_nop 1
	v_cvt_pk_bf16_f32 v176, v188, v189
	v_cvt_pk_bf16_f32 v177, v186, v187
	v_cvt_pk_bf16_f32 v178, v192, v193
	v_cvt_pk_bf16_f32 v179, v190, v191
	global_store_dwordx4 v[180:181], v[176:179], off offset:256
	s_nop 1
	v_mov_b32_e32 v136, v209
	v_mul_f32_e32 v136, v175, v136
	v_mad_i64_i32 v[176:177], s[44:45], v169, s53, v[152:153]
	v_lshl_add_u64 v[180:181], v[176:177], 0, v[156:157]
	v_pk_mul_f32 v[178:179], v[30:31], v[136:137] op_sel_hi:[1,0]
	v_pk_mul_f32 v[176:177], v[28:29], v[136:137] op_sel_hi:[1,0]
	v_pk_mul_f32 v[182:183], v[26:27], v[136:137] op_sel_hi:[1,0]
	v_pk_mul_f32 v[184:185], v[24:25], v[136:137] op_sel_hi:[1,0]
	v_cvt_pk_bf16_f32 v176, v176, v177
	v_cvt_pk_bf16_f32 v177, v178, v179
	v_pk_mul_f32 v[186:187], v[22:23], v[136:137] op_sel_hi:[1,0]
	v_cvt_pk_bf16_f32 v178, v184, v185
	v_cvt_pk_bf16_f32 v179, v182, v183
	v_pk_mul_f32 v[188:189], v[20:21], v[136:137] op_sel_hi:[1,0]
	v_pk_mul_f32 v[190:191], v[18:19], v[136:137] op_sel_hi:[1,0]
	v_pk_mul_f32 v[192:193], v[16:17], v[136:137] op_sel_hi:[1,0]
	global_store_dwordx4 v[180:181], v[176:179], off
	s_nop 1
	v_cvt_pk_bf16_f32 v176, v188, v189
	v_cvt_pk_bf16_f32 v177, v186, v187
	v_cvt_pk_bf16_f32 v178, v192, v193
	v_cvt_pk_bf16_f32 v179, v190, v191
	global_store_dwordx4 v[180:181], v[176:179], off offset:256
	s_nop 1
	v_mov_b32_e32 v136, v210
	v_mad_i64_i32 v[150:151], s[44:45], v168, s53, v[152:153]
	v_lshl_add_u64 v[156:157], v[150:151], 0, v[156:157]
	s_mov_b64 s[44:45], 0
	v_mul_f32_e32 v136, v175, v136
	v_pk_mul_f32 v[152:153], v[14:15], v[136:137] op_sel_hi:[1,0]
	v_pk_mul_f32 v[150:151], v[12:13], v[136:137] op_sel_hi:[1,0]
	v_pk_mul_f32 v[176:177], v[10:11], v[136:137] op_sel_hi:[1,0]
	v_pk_mul_f32 v[178:179], v[8:9], v[136:137] op_sel_hi:[1,0]
	v_cvt_pk_bf16_f32 v150, v150, v151
	v_cvt_pk_bf16_f32 v151, v152, v153
	v_pk_mul_f32 v[180:181], v[6:7], v[136:137] op_sel_hi:[1,0]
	v_cvt_pk_bf16_f32 v152, v178, v179
	v_cvt_pk_bf16_f32 v153, v176, v177
	v_pk_mul_f32 v[182:183], v[4:5], v[136:137] op_sel_hi:[1,0]
	v_pk_mul_f32 v[184:185], v[2:3], v[136:137] op_sel_hi:[1,0]
	v_pk_mul_f32 v[186:187], v[0:1], v[136:137] op_sel_hi:[1,0]
	global_store_dwordx4 v[156:157], v[150:153], off
	s_nop 1
	v_cvt_pk_bf16_f32 v150, v182, v183
	v_cvt_pk_bf16_f32 v151, v180, v181
	v_cvt_pk_bf16_f32 v152, v186, v187
	v_cvt_pk_bf16_f32 v153, v184, v185
	global_store_dwordx4 v[156:157], v[150:153], off offset:256

; #define PG8_STAGE(bufoff, gbase, voff) do { _Pragma("unroll") for (int _i = 0; _i < 2; ++_i) \
;         __builtin_amdgcn_global_load_lds((const unsigned*)((const char*)(gbase) + (voff)[_i]), (LAS unsigned*)(lds + (bufoff) + ldsw + _i * 8192), 16, 0, 0); } while (0)
; #define PG8_LDA(dst, b, h) do { _Pragma("unroll") for (int m = 0; m < 4; ++m) _Pragma("unroll") for (int k = 0; k < 2; ++k) dst[m][k] = *(const LAS bf16x8*)(lds + PG8_SA(b, h) + aoff + m * 2048 + k * 1024); } while (0)
; #define PG8_LDB(dst, b, h) do { _Pragma("unroll") for (int n = 0; n < 2; ++n) _Pragma("unroll") for (int k = 0; k < 2; ++k) dst[n][k] = *(const LAS bf16x8*)(lds + PG8_SB(b, h) + boff + n * 2048 + k * 1024); } while (0)
; #define PG8_MMA(ai, bj, At, Bt) do { __builtin_amdgcn_s_setprio(1); _Pragma("unroll") for (int m = 0; m < 4; ++m) _Pragma("unroll") for (int n = 0; n < 2; ++n) _Pragma("unroll") for (int k = 0; k < 2; ++k) \
;         acc[ai][bj][m][n] = __builtin_amdgcn_mfma_f32_16x16x32_bf16(Bt[n][k], At[m][k], acc[ai][bj][m][n], 0, 0, 0); __builtin_amdgcn_s_setprio(0); } while (0)
; #define PG8_WAIT_L(n) asm volatile("s_waitcnt lgkmcnt(" #n ")" ::: "memory")
; #define PG8_BAR __builtin_amdgcn_s_barrier()
; #define PG8_SCHED __builtin_amdgcn_sched_barrier(0)
; template <class Epi>
; __device__ __forceinline__ void gemm_phase(LAS unsigned char* lds, const Gemm g, const StaticOrder& S, const Epi& E) {
;     ...
;             PG8_LDB(B0, 0, 0); PG8_SCHED; PG8_LDA(At, 0, 0); PG8_STAGE(PG8_SA(1, 1), a1 + hstep, voffA);
;             PG8_WAIT_L(8); PG8_BAR; PG8_WAIT_L(0); PG8_MMA(0, 0, At, B0); PG8_BAR; PG8_SCHED;
;             PG8_LDB(B1, 0, 1); PG8_STAGE(PG8_SB(0, 0), b2, voffB);
;             PG8_BAR; PG8_WAIT_L(0); PG8_MMA(0, 1, At, B1); PG8_BAR;
;             PG8_LDA(At, 0, 1); PG8_STAGE(PG8_SA(0, 0), a2, voffA);
;             PG8_BAR; PG8_WAIT_L(0); PG8_MMA(1, 0, At, B0); PG8_BAR; PG8_SCHED;
.LBB0_796:
	ds_read_b128 v[144:147], v155
	ds_read_b128 v[148:151], v155 offset:1024
	ds_read_b128 v[160:163], v155 offset:2048
	ds_read_b128 v[164:167], v155 offset:3072
	s_add_u32 s42, s40, 0xfff80080
	s_addc_u32 s43, s41, -1
	s_cmp_eq_u32 s58, 28
	s_cselect_b32 s45, s31, s43
	s_cselect_b32 s44, s54, s42
	s_cselect_b32 s43, s9, s57
	s_cselect_b32 s42, s55, s56
	v_lshl_add_u64 v[200:201], s[40:41], 0, v[136:137]
	s_add_i32 m0, s27, 0xc000
	ds_read_b128 v[168:171], v156
	ds_read_b128 v[172:175], v156 offset:1024
	ds_read_b128 v[176:179], v156 offset:2048
	ds_read_b128 v[180:183], v156 offset:3072
	ds_read_b128 v[184:187], v156 offset:4096
	ds_read_b128 v[188:191], v156 offset:5120
	ds_read_b128 v[192:195], v156 offset:6144
	ds_read_b128 v[196:199], v156 offset:7168
	global_load_lds_dwordx4 v[200:201], off
	v_lshl_add_u64 v[200:201], s[40:41], 0, v[138:139]
	s_add_i32 m0, s27, 0xe000
	s_nop 0
	global_load_lds_dwordx4 v[200:201], off
	s_waitcnt lgkmcnt(8)
	s_barrier
	s_waitcnt lgkmcnt(0)
	s_setprio 1
	s_waitcnt lgkmcnt(0)
	v_mfma_f32_16x16x32_bf16 v[124:127], v[144:147], v[168:171], v[124:127]
	v_mfma_f32_16x16x32_bf16 v[120:123], v[160:163], v[168:171], v[120:123]
	v_mfma_f32_16x16x32_bf16 v[108:111], v[144:147], v[176:179], v[108:111]
	v_mfma_f32_16x16x32_bf16 v[104:107], v[160:163], v[176:179], v[104:107]
	v_mfma_f32_16x16x32_bf16 v[92:95], v[144:147], v[184:187], v[92:95]
	v_mfma_f32_16x16x32_bf16 v[88:91], v[160:163], v[184:187], v[88:91]
	v_mfma_f32_16x16x32_bf16 v[76:79], v[144:147], v[192:195], v[76:79]
	v_mfma_f32_16x16x32_bf16 v[72:75], v[160:163], v[192:195], v[72:75]
	v_mfma_f32_16x16x32_bf16 v[124:127], v[148:151], v[172:175], v[124:127]
	v_mfma_f32_16x16x32_bf16 v[120:123], v[164:167], v[172:175], v[120:123]
	v_mfma_f32_16x16x32_bf16 v[108:111], v[148:151], v[180:183], v[108:111]
	v_mfma_f32_16x16x32_bf16 v[104:107], v[164:167], v[180:183], v[104:107]
	v_mfma_f32_16x16x32_bf16 v[92:95], v[148:151], v[188:191], v[92:95]
	v_mfma_f32_16x16x32_bf16 v[88:91], v[164:167], v[188:191], v[88:91]
	v_mfma_f32_16x16x32_bf16 v[76:79], v[148:151], v[196:199], v[76:79]
	v_mfma_f32_16x16x32_bf16 v[72:75], v[164:167], v[196:199], v[72:75]
	s_setprio 0
	s_barrier
	s_add_i32 s59, s50, s23
	v_lshl_add_u64 v[216:217], s[42:43], 0, v[132:133]
	s_mov_b32 m0, s59
	ds_read_b128 v[200:203], v157
	ds_read_b128 v[204:207], v157 offset:1024
	ds_read_b128 v[208:211], v157 offset:2048
	ds_read_b128 v[212:215], v157 offset:3072
	global_load_lds_dwordx4 v[216:217], off
	v_lshl_add_u64 v[218:219], s[42:43], 0, v[128:129]
	s_add_i32 m0, s59, 0x2000
	s_nop 0
	global_load_lds_dwordx4 v[218:219], off
	s_barrier
	s_waitcnt lgkmcnt(0)
	s_setprio 1
	s_waitcnt lgkmcnt(0)
	v_mfma_f32_16x16x32_bf16 v[116:119], v[200:203], v[168:171], v[116:119]
	v_mfma_f32_16x16x32_bf16 v[112:115], v[208:211], v[168:171], v[112:115]
	v_mfma_f32_16x16x32_bf16 v[100:103], v[200:203], v[176:179], v[100:103]
	v_mfma_f32_16x16x32_bf16 v[96:99], v[208:211], v[176:179], v[96:99]
	v_mfma_f32_16x16x32_bf16 v[84:87], v[200:203], v[184:187], v[84:87]
	v_mfma_f32_16x16x32_bf16 v[80:83], v[208:211], v[184:187], v[80:83]
	v_mfma_f32_16x16x32_bf16 v[68:71], v[200:203], v[192:195], v[68:71]
	v_mfma_f32_16x16x32_bf16 v[64:67], v[208:211], v[192:195], v[64:67]
	v_mfma_f32_16x16x32_bf16 v[116:119], v[204:207], v[172:175], v[116:119]
	v_mfma_f32_16x16x32_bf16 v[112:115], v[212:215], v[172:175], v[112:115]
	v_mfma_f32_16x16x32_bf16 v[100:103], v[204:207], v[180:183], v[100:103]
	v_mfma_f32_16x16x32_bf16 v[96:99], v[212:215], v[180:183], v[96:99]
	v_mfma_f32_16x16x32_bf16 v[84:87], v[204:207], v[188:191], v[84:87]
	v_mfma_f32_16x16x32_bf16 v[80:83], v[212:215], v[188:191], v[80:83]
	v_mfma_f32_16x16x32_bf16 v[68:71], v[204:207], v[196:199], v[68:71]
	v_mfma_f32_16x16x32_bf16 v[64:67], v[212:215], v[196:199], v[64:67]
	s_setprio 0
	s_mov_b32 m0, s27
	v_lshl_add_u64 v[220:221], s[44:45], 0, v[134:135]
	s_barrier
	ds_read_b128 v[168:171], v156 offset:16384
	ds_read_b128 v[172:175], v156 offset:17408
	ds_read_b128 v[176:179], v156 offset:18432
	ds_read_b128 v[180:183], v156 offset:19456
	ds_read_b128 v[184:187], v156 offset:20480
	ds_read_b128 v[188:191], v156 offset:21504
	ds_read_b128 v[192:195], v156 offset:22528
	ds_read_b128 v[196:199], v156 offset:23552
	global_load_lds_dwordx4 v[220:221], off
	v_lshl_add_u64 v[222:223], s[44:45], 0, v[130:131]
	s_mov_b32 m0, s28
	s_nop 0
	global_load_lds_dwordx4 v[222:223], off
	s_barrier
	s_waitcnt lgkmcnt(0)
	s_setprio 1
	s_waitcnt lgkmcnt(0)
	v_mfma_f32_16x16x32_bf16 v[60:63], v[144:147], v[168:171], v[60:63]
	v_mfma_f32_16x16x32_bf16 v[56:59], v[160:163], v[168:171], v[56:59]
	v_mfma_f32_16x16x32_bf16 v[44:47], v[144:147], v[176:179], v[44:47]
	v_mfma_f32_16x16x32_bf16 v[40:43], v[160:163], v[176:179], v[40:43]
	v_mfma_f32_16x16x32_bf16 v[28:31], v[144:147], v[184:187], v[28:31]
	v_mfma_f32_16x16x32_bf16 v[24:27], v[160:163], v[184:187], v[24:27]
	v_mfma_f32_16x16x32_bf16 v[12:15], v[144:147], v[192:195], v[12:15]
	v_mfma_f32_16x16x32_bf16 v[8:11], v[160:163], v[192:195], v[8:11]
	v_mfma_f32_16x16x32_bf16 v[60:63], v[148:151], v[172:175], v[60:63]
	v_mfma_f32_16x16x32_bf16 v[56:59], v[164:167], v[172:175], v[56:59]
	v_mfma_f32_16x16x32_bf16 v[44:47], v[148:151], v[180:183], v[44:47]
	v_mfma_f32_16x16x32_bf16 v[40:43], v[164:167], v[180:183], v[40:43]
	v_mfma_f32_16x16x32_bf16 v[28:31], v[148:151], v[188:191], v[28:31]
	v_mfma_f32_16x16x32_bf16 v[24:27], v[164:167], v[188:191], v[24:27]
	v_mfma_f32_16x16x32_bf16 v[12:15], v[148:151], v[196:199], v[12:15]
	v_mfma_f32_16x16x32_bf16 v[8:11], v[164:167], v[196:199], v[8:11]
	s_setprio 0
	s_barrier
; #define PG8_STAGE(bufoff, gbase, voff) do { _Pragma("unroll") for (int _i = 0; _i < 2; ++_i) \
;         __builtin_amdgcn_global_load_lds((const unsigned*)((const char*)(gbase) + (voff)[_i]), (LAS unsigned*)(lds + (bufoff) + ldsw + _i * 8192), 16, 0, 0); } while (0)
; #define PG8_LDA(dst, b, h) do { _Pragma("unroll") for (int m = 0; m < 4; ++m) _Pragma("unroll") for (int k = 0; k < 2; ++k) dst[m][k] = *(const LAS bf16x8*)(lds + PG8_SA(b, h) + aoff + m * 2048 + k * 1024); } while (0)
; #define PG8_LDB(dst, b, h) do { _Pragma("unroll") for (int n = 0; n < 2; ++n) _Pragma("unroll") for (int k = 0; k < 2; ++k) dst[n][k] = *(const LAS bf16x8*)(lds + PG8_SB(b, h) + boff + n * 2048 + k * 1024); } while (0)
; #define PG8_MMA(ai, bj, At, Bt) do { __builtin_amdgcn_s_setprio(1); _Pragma("unroll") for (int m = 0; m < 4; ++m) _Pragma("unroll") for (int n = 0; n < 2; ++n) _Pragma("unroll") for (int k = 0; k < 2; ++k) \
;         acc[ai][bj][m][n] = __builtin_amdgcn_mfma_f32_16x16x32_bf16(Bt[n][k], At[m][k], acc[ai][bj][m][n], 0, 0, 0); __builtin_amdgcn_s_setprio(0); } while (0)
; #define PG8_WAIT_V(n) asm volatile("s_waitcnt vmcnt(" #n ")" ::: "memory")
; #define PG8_WAIT_L(n) asm volatile("s_waitcnt lgkmcnt(" #n ")" ::: "memory")
; #define PG8_BAR __builtin_amdgcn_s_barrier()
; #define PG8_SCHED __builtin_amdgcn_sched_barrier(0)
; template <class Epi>
; __device__ __forceinline__ void gemm_phase(LAS unsigned char* lds, const Gemm g, const StaticOrder& S, const Epi& E) {
;     ...
;             PG8_STAGE(PG8_SB(0, 1), b2 + hstep, voffB);
;             PG8_WAIT_V(6); PG8_BAR; PG8_MMA(1, 1, At, B1); PG8_BAR;
;             PG8_LDB(B0, 1, 0); PG8_SCHED; PG8_LDA(At, 1, 0); PG8_STAGE(PG8_SA(0, 1), a2 + hstep, voffA);
;             PG8_WAIT_L(8); PG8_BAR; PG8_WAIT_L(0); PG8_MMA(0, 0, At, B0); PG8_BAR; PG8_SCHED;
;             PG8_LDB(B1, 1, 1); PG8_STAGE(PG8_SB(1, 0), b3, voffB);
;             PG8_BAR; PG8_WAIT_L(0); PG8_MMA(0, 1, At, B1); PG8_BAR;
;             PG8_LDA(At, 1, 1); PG8_STAGE(PG8_SA(1, 0), a3, voffA);
	s_add_u32 s60, s42, 0x80000
	s_addc_u32 s61, s43, 0
	s_add_i32 s59, s51, s23
	v_lshl_add_u64 v[144:145], s[60:61], 0, v[132:133]
	s_mov_b32 m0, s59
	s_nop 0
	global_load_lds_dwordx4 v[144:145], off
	v_lshl_add_u64 v[144:145], s[60:61], 0, v[128:129]
	s_add_i32 m0, s59, 0x2000
	s_nop 0
	global_load_lds_dwordx4 v[144:145], off
	s_waitcnt vmcnt(6)
	s_barrier
	s_setprio 1
	v_mfma_f32_16x16x32_bf16 v[52:55], v[200:203], v[168:171], v[52:55]
	v_mfma_f32_16x16x32_bf16 v[48:51], v[208:211], v[168:171], v[48:51]
	v_mfma_f32_16x16x32_bf16 v[36:39], v[200:203], v[176:179], v[36:39]
	v_mfma_f32_16x16x32_bf16 v[32:35], v[208:211], v[176:179], v[32:35]
	v_mfma_f32_16x16x32_bf16 v[20:23], v[200:203], v[184:187], v[20:23]
	v_mfma_f32_16x16x32_bf16 v[16:19], v[208:211], v[184:187], v[16:19]
	v_mfma_f32_16x16x32_bf16 v[4:7], v[200:203], v[192:195], v[4:7]
	v_mfma_f32_16x16x32_bf16 v[0:3], v[208:211], v[192:195], v[0:3]
	v_mfma_f32_16x16x32_bf16 v[52:55], v[204:207], v[172:175], v[52:55]
	v_mfma_f32_16x16x32_bf16 v[48:51], v[212:215], v[172:175], v[48:51]
	v_mfma_f32_16x16x32_bf16 v[36:39], v[204:207], v[180:183], v[36:39]
	v_mfma_f32_16x16x32_bf16 v[32:35], v[212:215], v[180:183], v[32:35]
	v_mfma_f32_16x16x32_bf16 v[20:23], v[204:207], v[188:191], v[20:23]
	v_mfma_f32_16x16x32_bf16 v[16:19], v[212:215], v[188:191], v[16:19]
	v_mfma_f32_16x16x32_bf16 v[4:7], v[204:207], v[196:199], v[4:7]
	v_mfma_f32_16x16x32_bf16 v[0:3], v[212:215], v[196:199], v[0:3]
	s_setprio 0
	s_add_i32 s59, 0, 0x18000
	v_add_u32_e32 v164, s59, v153
	s_barrier
	ds_read_b128 v[144:147], v164
	ds_read_b128 v[148:151], v164 offset:1024
	ds_read_b128 v[160:163], v164 offset:2048
	ds_read_b128 v[164:167], v164 offset:3072
	s_add_u32 s44, s44, 0x80000
	s_addc_u32 s45, s45, 0
	s_mov_b32 m0, s29
	v_lshl_add_u64 v[200:201], s[44:45], 0, v[134:135]
	ds_read_b128 v[168:171], v156 offset:32768
	ds_read_b128 v[172:175], v156 offset:33792
	ds_read_b128 v[176:179], v156 offset:34816
	ds_read_b128 v[180:183], v156 offset:35840
	ds_read_b128 v[184:187], v156 offset:36864
	ds_read_b128 v[188:191], v156 offset:37888
	ds_read_b128 v[192:195], v156 offset:38912
	ds_read_b128 v[196:199], v156 offset:39936
	global_load_lds_dwordx4 v[200:201], off
	v_lshl_add_u64 v[200:201], s[44:45], 0, v[130:131]
	s_mov_b32 m0, s33
	s_nop 0
	global_load_lds_dwordx4 v[200:201], off
	s_waitcnt lgkmcnt(8)
	s_barrier
	s_waitcnt lgkmcnt(0)
	s_setprio 1
	s_waitcnt lgkmcnt(0)
	v_mfma_f32_16x16x32_bf16 v[124:127], v[144:147], v[168:171], v[124:127]
	v_mfma_f32_16x16x32_bf16 v[120:123], v[160:163], v[168:171], v[120:123]
	v_mfma_f32_16x16x32_bf16 v[108:111], v[144:147], v[176:179], v[108:111]
	v_mfma_f32_16x16x32_bf16 v[104:107], v[160:163], v[176:179], v[104:107]
	v_mfma_f32_16x16x32_bf16 v[92:95], v[144:147], v[184:187], v[92:95]
	v_mfma_f32_16x16x32_bf16 v[88:91], v[160:163], v[184:187], v[88:91]
	v_mfma_f32_16x16x32_bf16 v[76:79], v[144:147], v[192:195], v[76:79]
	v_mfma_f32_16x16x32_bf16 v[72:75], v[160:163], v[192:195], v[72:75]
	v_mfma_f32_16x16x32_bf16 v[124:127], v[148:151], v[172:175], v[124:127]
	v_mfma_f32_16x16x32_bf16 v[120:123], v[164:167], v[172:175], v[120:123]
	v_mfma_f32_16x16x32_bf16 v[108:111], v[148:151], v[180:183], v[108:111]
	v_mfma_f32_16x16x32_bf16 v[104:107], v[164:167], v[180:183], v[104:107]
	v_mfma_f32_16x16x32_bf16 v[92:95], v[148:151], v[188:191], v[92:95]
	v_mfma_f32_16x16x32_bf16 v[88:91], v[164:167], v[188:191], v[88:91]
	v_mfma_f32_16x16x32_bf16 v[76:79], v[148:151], v[196:199], v[76:79]
	v_mfma_f32_16x16x32_bf16 v[72:75], v[164:167], v[196:199], v[72:75]
	s_setprio 0
	s_barrier
	s_add_i32 s44, 0, 0x1c000
	s_add_i32 s45, s59, s23
	v_add_u32_e32 v212, s44, v153
	v_lshl_add_u64 v[216:217], v[216:217], 0, s[2:3]
	s_mov_b32 m0, s45
	ds_read_b128 v[200:203], v212
	ds_read_b128 v[204:207], v212 offset:1024
	ds_read_b128 v[208:211], v212 offset:2048
	ds_read_b128 v[212:215], v212 offset:3072
	global_load_lds_dwordx4 v[216:217], off
	v_lshl_add_u64 v[216:217], v[218:219], 0, s[2:3]
	s_add_i32 m0, s45, 0x2000
	s_nop 0
	global_load_lds_dwordx4 v[216:217], off
	s_barrier
	s_waitcnt lgkmcnt(0)
	s_setprio 1
	s_waitcnt lgkmcnt(0)
	v_mfma_f32_16x16x32_bf16 v[116:119], v[200:203], v[168:171], v[116:119]
	v_mfma_f32_16x16x32_bf16 v[112:115], v[208:211], v[168:171], v[112:115]
	v_mfma_f32_16x16x32_bf16 v[100:103], v[200:203], v[176:179], v[100:103]
	v_mfma_f32_16x16x32_bf16 v[96:99], v[208:211], v[176:179], v[96:99]
	v_mfma_f32_16x16x32_bf16 v[84:87], v[200:203], v[184:187], v[84:87]
	v_mfma_f32_16x16x32_bf16 v[80:83], v[208:211], v[184:187], v[80:83]
	v_mfma_f32_16x16x32_bf16 v[68:71], v[200:203], v[192:195], v[68:71]
	v_mfma_f32_16x16x32_bf16 v[64:67], v[208:211], v[192:195], v[64:67]
	v_mfma_f32_16x16x32_bf16 v[116:119], v[204:207], v[172:175], v[116:119]
	v_mfma_f32_16x16x32_bf16 v[112:115], v[212:215], v[172:175], v[112:115]
	v_mfma_f32_16x16x32_bf16 v[100:103], v[204:207], v[180:183], v[100:103]
	v_mfma_f32_16x16x32_bf16 v[96:99], v[212:215], v[180:183], v[96:99]
	v_mfma_f32_16x16x32_bf16 v[84:87], v[204:207], v[188:191], v[84:87]
	v_mfma_f32_16x16x32_bf16 v[80:83], v[212:215], v[188:191], v[80:83]
	v_mfma_f32_16x16x32_bf16 v[68:71], v[204:207], v[196:199], v[68:71]
	v_mfma_f32_16x16x32_bf16 v[64:67], v[212:215], v[196:199], v[64:67]
	s_setprio 0
	s_mov_b32 m0, s46
	v_lshl_add_u64 v[216:217], v[220:221], 0, s[2:3]
	s_barrier
	ds_read_b128 v[168:171], v156 offset:49152
	ds_read_b128 v[172:175], v156 offset:50176
	ds_read_b128 v[176:179], v156 offset:51200
	ds_read_b128 v[180:183], v156 offset:52224
	ds_read_b128 v[184:187], v156 offset:53248
	ds_read_b128 v[188:191], v156 offset:54272
	ds_read_b128 v[192:195], v156 offset:55296
	ds_read_b128 v[196:199], v156 offset:56320
	global_load_lds_dwordx4 v[216:217], off
	v_lshl_add_u64 v[216:217], v[222:223], 0, s[2:3]
	s_mov_b32 m0, s47
	s_nop 0
	global_load_lds_dwordx4 v[216:217], off
	s_barrier
; __device__ __forceinline__ float fast_rcp(float x) { return __builtin_amdgcn_rcpf(x); }
; __device__ __forceinline__ float fast_exp2(float x) { return __builtin_amdgcn_exp2f(x); }
; #define PG8_STAGE(bufoff, gbase, voff) do { _Pragma("unroll") for (int _i = 0; _i < 2; ++_i) \
;         __builtin_amdgcn_global_load_lds((const unsigned*)((const char*)(gbase) + (voff)[_i]), (LAS unsigned*)(lds + (bufoff) + ldsw + _i * 8192), 16, 0, 0); } while (0)
; #define PG8_MMA(ai, bj, At, Bt) do { __builtin_amdgcn_s_setprio(1); _Pragma("unroll") for (int m = 0; m < 4; ++m) _Pragma("unroll") for (int n = 0; n < 2; ++n) _Pragma("unroll") for (int k = 0; k < 2; ++k) \
;         acc[ai][bj][m][n] = __builtin_amdgcn_mfma_f32_16x16x32_bf16(Bt[n][k], At[m][k], acc[ai][bj][m][n], 0, 0, 0); __builtin_amdgcn_s_setprio(0); } while (0)
; #define PG8_WAIT_V(n) asm volatile("s_waitcnt vmcnt(" #n ")" ::: "memory")
; #define PG8_WAIT_L(n) asm volatile("s_waitcnt lgkmcnt(" #n ")" ::: "memory")
; #define PG8_BAR __builtin_amdgcn_s_barrier()
; #define PG8_SCHED __builtin_amdgcn_sched_barrier(0)
; template <class Epi>
; __device__ __forceinline__ void gemm_phase(LAS unsigned char* lds, const Gemm g, const StaticOrder& S, const Epi& E) {
;     ...
;             PG8_BAR; PG8_WAIT_L(0); PG8_MMA(1, 0, At, B0); PG8_BAR; PG8_SCHED;
;             PG8_STAGE(PG8_SB(1, 1), b3 + hstep, voffB);
;             PG8_WAIT_V(6); PG8_BAR; PG8_MMA(1, 1, At, B1); PG8_BAR;
;     __device__ __forceinline__ void operator()(const f32x4 (&acc)[2][2][4][2], const Unit& u, int wr, int wc, int fr, int fq) const {
;         const int row0 = u.pm * BM + wr * 64 + fr, col0 = u.pn * HALF + wc * 32 + 8 * fq;
; #pragma unroll
;         for (int ai = 0; ai < 2; ++ai)
; #pragma unroll
;             for (int m = 0; m < 4; ++m) { bf16_t* rowp = O + (size_t)(row0 + ai * HALF + m * 16) * DFF + col0;
;                 const float r = rs[row0 + ai * HALF + m * 16], r2 = r * r;
;                 f32x4 h0, h1;
; #pragma unroll
;                 for (int j = 0; j < 4; ++j) {
;                     const float g0 = acc[ai][0][m][0][j], g1 = acc[ai][0][m][1][j];
;                     h0[j] = g0 * r2 * fast_rcp(1.0f + fast_exp2(g0 * (-LOG2E * r))) * acc[ai][1][m][0][j];
;                     h1[j] = g1 * r2 * fast_rcp(1.0f + fast_exp2(g1 * (-LOG2E * r))) * acc[ai][1][m][1][j]; }
;                 *(u32x4*)rowp = pack8(h0, h1); }
	s_waitcnt lgkmcnt(0)
	s_setprio 1
	s_waitcnt lgkmcnt(0)
	v_mfma_f32_16x16x32_bf16 v[60:63], v[144:147], v[168:171], v[60:63]
	v_mfma_f32_16x16x32_bf16 v[56:59], v[160:163], v[168:171], v[56:59]
	v_mfma_f32_16x16x32_bf16 v[44:47], v[144:147], v[176:179], v[44:47]
	v_mfma_f32_16x16x32_bf16 v[40:43], v[160:163], v[176:179], v[40:43]
	v_mfma_f32_16x16x32_bf16 v[28:31], v[144:147], v[184:187], v[28:31]
	v_mfma_f32_16x16x32_bf16 v[24:27], v[160:163], v[184:187], v[24:27]
	v_mfma_f32_16x16x32_bf16 v[12:15], v[144:147], v[192:195], v[12:15]
	v_mfma_f32_16x16x32_bf16 v[8:11], v[160:163], v[192:195], v[8:11]
	v_mfma_f32_16x16x32_bf16 v[60:63], v[148:151], v[172:175], v[60:63]
	v_mfma_f32_16x16x32_bf16 v[56:59], v[164:167], v[172:175], v[56:59]
	v_mfma_f32_16x16x32_bf16 v[44:47], v[148:151], v[180:183], v[44:47]
	v_mfma_f32_16x16x32_bf16 v[40:43], v[164:167], v[180:183], v[40:43]
	v_mfma_f32_16x16x32_bf16 v[28:31], v[148:151], v[188:191], v[28:31]
	v_mfma_f32_16x16x32_bf16 v[24:27], v[164:167], v[188:191], v[24:27]
	v_mfma_f32_16x16x32_bf16 v[12:15], v[148:151], v[196:199], v[12:15]
	v_mfma_f32_16x16x32_bf16 v[8:11], v[164:167], v[196:199], v[8:11]
	s_setprio 0
	s_barrier
	s_add_u32 s42, s42, 0x80080
	s_addc_u32 s43, s43, 0
	s_add_i32 s44, s44, s23
	v_lshl_add_u64 v[144:145], s[42:43], 0, v[132:133]
	s_mov_b32 m0, s44
	s_nop 0
	global_load_lds_dwordx4 v[144:145], off
	v_lshl_add_u64 v[144:145], s[42:43], 0, v[128:129]
	s_add_i32 m0, s44, 0x2000
	s_nop 0
	global_load_lds_dwordx4 v[144:145], off
	s_waitcnt vmcnt(6)
	s_barrier
	s_setprio 1
	v_mfma_f32_16x16x32_bf16 v[52:55], v[200:203], v[168:171], v[52:55]
	v_mfma_f32_16x16x32_bf16 v[48:51], v[208:211], v[168:171], v[48:51]
	v_mfma_f32_16x16x32_bf16 v[36:39], v[200:203], v[176:179], v[36:39]
	v_mfma_f32_16x16x32_bf16 v[32:35], v[208:211], v[176:179], v[32:35]
	v_mfma_f32_16x16x32_bf16 v[20:23], v[200:203], v[184:187], v[20:23]
	v_mfma_f32_16x16x32_bf16 v[16:19], v[208:211], v[184:187], v[16:19]
	v_mfma_f32_16x16x32_bf16 v[4:7], v[200:203], v[192:195], v[4:7]
	v_mfma_f32_16x16x32_bf16 v[0:3], v[208:211], v[192:195], v[0:3]
	v_mfma_f32_16x16x32_bf16 v[52:55], v[204:207], v[172:175], v[52:55]
	v_mfma_f32_16x16x32_bf16 v[48:51], v[212:215], v[172:175], v[48:51]
	v_mfma_f32_16x16x32_bf16 v[36:39], v[204:207], v[180:183], v[36:39]
	v_mfma_f32_16x16x32_bf16 v[32:35], v[212:215], v[180:183], v[32:35]
	v_mfma_f32_16x16x32_bf16 v[20:23], v[204:207], v[188:191], v[20:23]
	v_mfma_f32_16x16x32_bf16 v[16:19], v[212:215], v[188:191], v[16:19]
	v_mfma_f32_16x16x32_bf16 v[4:7], v[204:207], v[196:199], v[4:7]
	v_mfma_f32_16x16x32_bf16 v[0:3], v[212:215], v[196:199], v[0:3]
	s_setprio 0
	s_add_i32 s58, s58, 2
	s_add_u32 s40, s40, 0x100
	s_addc_u32 s41, s41, 0
	s_add_u32 s56, s56, 0x100
	s_addc_u32 s57, s57, 0
	s_cmp_gt_u32 s58, 29
	s_barrier
	s_cbranch_scc0 .LBB0_796
	v_lshl_add_u32 v144, s38, 8, v152
	v_ashrrev_i32_e32 v145, 31, v144
	v_lshl_add_u64 v[150:151], v[144:145], 2, s[14:15]
	global_load_dword v145, v[150:151], off
	global_load_dword v204, v[150:151], off offset:64
	global_load_dword v205, v[150:151], off offset:128
	global_load_dword v206, v[150:151], off offset:192
	global_load_dword v207, v[150:151], off offset:512
	global_load_dword v208, v[150:151], off offset:576
	global_load_dword v209, v[150:151], off offset:640
	global_load_dword v210, v[150:151], off offset:704
	v_lshl_or_b32 v148, s53, 7, v154
	v_mov_b64_e32 v[146:147], s[20:21]
	v_ashrrev_i32_e32 v149, 31, v148
	v_mad_i64_i32 v[160:161], s[40:41], v144, s52, v[146:147]
	v_lshlrev_b64 v[148:149], 1, v[148:149]
	v_lshl_add_u64 v[160:161], v[160:161], 0, v[148:149]
	s_and_b64 vcc, exec, s[6:7]
	s_mov_b32 s53, s8
	s_mov_b32 s38, s30
	s_mov_b64 s[42:43], s[36:37]
	s_waitcnt vmcnt(0)
	v_mul_f32_e32 v162, v145, v145
	v_mul_f32_e32 v145, 0xbfb8aa3b, v145
	v_mul_f32_e32 v163, v124, v162
	v_mul_f32_e32 v164, v120, v162
	v_mul_f32_e32 v120, v120, v145
	v_mul_f32_e32 v165, v125, v162
	v_mul_f32_e32 v125, v125, v145
	v_mul_f32_e32 v166, v121, v162
	v_mul_f32_e32 v121, v121, v145
	v_mul_f32_e32 v167, v126, v162
	v_mul_f32_e32 v126, v126, v145
	v_mul_f32_e32 v168, v122, v162
	v_mul_f32_e32 v122, v122, v145
	v_mul_f32_e32 v169, v127, v162
	v_mul_f32_e32 v127, v127, v145
	v_mul_f32_e32 v162, v123, v162
	v_mul_f32_e32 v123, v123, v145
	v_mul_f32_e32 v124, v124, v145
	v_exp_f32_e32 v120, v120
	v_exp_f32_e32 v125, v125
	v_exp_f32_e32 v121, v121
	v_exp_f32_e32 v126, v126
	v_exp_f32_e32 v122, v122
	v_exp_f32_e32 v127, v127
	v_exp_f32_e32 v123, v123
	v_exp_f32_e32 v124, v124
	v_add_f32_e32 v120, 1.0, v120
	v_add_f32_e32 v125, 1.0, v125
	v_add_f32_e32 v121, 1.0, v121
	v_add_f32_e32 v126, 1.0, v126
	v_add_f32_e32 v122, 1.0, v122
	v_add_f32_e32 v127, 1.0, v127
	v_add_f32_e32 v123, 1.0, v123
	v_add_f32_e32 v124, 1.0, v124
	v_rcp_f32_e32 v120, v120
	v_rcp_f32_e32 v125, v125
	v_rcp_f32_e32 v121, v121
	v_rcp_f32_e32 v126, v126
	v_rcp_f32_e32 v122, v122
	v_rcp_f32_e32 v127, v127
	v_rcp_f32_e32 v123, v123
	v_rcp_f32_e32 v124, v124
	v_mul_f32_e32 v120, v164, v120
	v_mul_f32_e32 v125, v165, v125
	v_mul_f32_e32 v121, v166, v121
	v_mul_f32_e32 v126, v167, v126
	v_mul_f32_e32 v122, v168, v122
	v_mul_f32_e32 v127, v169, v127
	v_mul_f32_e32 v123, v162, v123
	v_mul_f32_e32 v124, v163, v124
	v_mul_f32_e32 v120, v112, v120
	v_mul_f32_e32 v112, v117, v125
	v_mul_f32_e32 v117, v113, v121
	v_mul_f32_e32 v113, v118, v126
	v_mul_f32_e32 v118, v114, v122
	v_mul_f32_e32 v114, v119, v127
	v_mul_f32_e32 v115, v115, v123
	v_mul_f32_e32 v116, v116, v124
	v_cvt_pk_bf16_f32 v112, v116, v112
	v_cvt_pk_bf16_f32 v113, v113, v114
	v_cvt_pk_bf16_f32 v114, v120, v117
	v_cvt_pk_bf16_f32 v115, v118, v115
; __device__ __forceinline__ float fast_rcp(float x) { return __builtin_amdgcn_rcpf(x); }
; __device__ __forceinline__ float fast_exp2(float x) { return __builtin_amdgcn_exp2f(x); }
; __device__ __forceinline__ u32x4 pack8(f32x4 v0, f32x4 v1) { u32x4 w; w.x = cvt_pk_bf16(v0[0], v0[1]); w.y = cvt_pk_bf16(v0[2], v0[3]); w.z = cvt_pk_bf16(v1[0], v1[1]); w.w = cvt_pk_bf16(v1[2], v1[3]); return w; }
;     __device__ __forceinline__ void operator()(const f32x4 (&acc)[2][2][4][2], const Unit& u, int wr, int wc, int fr, int fq) const {
;     ...
;         for (int ai = 0; ai < 2; ++ai)
; #pragma unroll
;             for (int m = 0; m < 4; ++m) { bf16_t* rowp = O + (size_t)(row0 + ai * HALF + m * 16) * DFF + col0;
;                 const float r = rs[row0 + ai * HALF + m * 16], r2 = r * r;
;                 f32x4 h0, h1;
; #pragma unroll
;                 for (int j = 0; j < 4; ++j) {
;                     const float g0 = acc[ai][0][m][0][j], g1 = acc[ai][0][m][1][j];
;                     h0[j] = g0 * r2 * fast_rcp(1.0f + fast_exp2(g0 * (-LOG2E * r))) * acc[ai][1][m][0][j];
;                     h1[j] = g1 * r2 * fast_rcp(1.0f + fast_exp2(g1 * (-LOG2E * r))) * acc[ai][1][m][1][j]; }
;                 *(u32x4*)rowp = pack8(h0, h1); }
	global_store_dwordx4 v[160:161], v[112:115], off
	s_nop 1
	v_mov_b32_e32 v114, v204
	s_nop 0
	v_or_b32_e32 v112, 16, v144
	v_mad_i64_i32 v[112:113], s[40:41], v112, s52, v[146:147]
	v_lshl_add_u64 v[112:113], v[112:113], 0, v[148:149]
	v_mul_f32_e32 v115, v114, v114
	v_mul_f32_e32 v114, 0xbfb8aa3b, v114
	v_mul_f32_e32 v116, v108, v115
	v_mul_f32_e32 v117, v104, v115
	v_mul_f32_e32 v104, v104, v114
	v_mul_f32_e32 v118, v109, v115
	v_mul_f32_e32 v109, v109, v114
	v_mul_f32_e32 v119, v105, v115
	v_mul_f32_e32 v105, v105, v114
	v_mul_f32_e32 v120, v110, v115
	v_mul_f32_e32 v110, v110, v114
	v_mul_f32_e32 v121, v106, v115
	v_mul_f32_e32 v106, v106, v114
	v_mul_f32_e32 v122, v111, v115
	v_mul_f32_e32 v111, v111, v114
	v_mul_f32_e32 v115, v107, v115
	v_mul_f32_e32 v107, v107, v114
	v_mul_f32_e32 v108, v108, v114
	v_exp_f32_e32 v104, v104
	v_exp_f32_e32 v109, v109
	v_exp_f32_e32 v105, v105
	v_exp_f32_e32 v110, v110
	v_exp_f32_e32 v106, v106
	v_exp_f32_e32 v111, v111
	v_exp_f32_e32 v107, v107
	v_exp_f32_e32 v108, v108
	v_add_f32_e32 v104, 1.0, v104
	v_add_f32_e32 v109, 1.0, v109
	v_add_f32_e32 v105, 1.0, v105
	v_add_f32_e32 v110, 1.0, v110
	v_add_f32_e32 v106, 1.0, v106
	v_add_f32_e32 v111, 1.0, v111
	v_add_f32_e32 v107, 1.0, v107
	v_add_f32_e32 v108, 1.0, v108
	v_rcp_f32_e32 v104, v104
	v_rcp_f32_e32 v109, v109
	v_rcp_f32_e32 v105, v105
	v_rcp_f32_e32 v110, v110
	v_rcp_f32_e32 v106, v106
	v_rcp_f32_e32 v111, v111
	v_rcp_f32_e32 v107, v107
	v_rcp_f32_e32 v108, v108
	v_mul_f32_e32 v104, v117, v104
	v_mul_f32_e32 v109, v118, v109
	v_mul_f32_e32 v105, v119, v105
	v_mul_f32_e32 v110, v120, v110
	v_mul_f32_e32 v106, v121, v106
	v_mul_f32_e32 v111, v122, v111
	v_mul_f32_e32 v107, v115, v107
	v_mul_f32_e32 v108, v116, v108
	v_mul_f32_e32 v104, v96, v104
	v_mul_f32_e32 v96, v101, v109
	v_mul_f32_e32 v101, v97, v105
	v_mul_f32_e32 v97, v102, v110
	v_mul_f32_e32 v102, v98, v106
	v_mul_f32_e32 v98, v103, v111
	v_mul_f32_e32 v99, v99, v107
	v_mul_f32_e32 v100, v100, v108
	v_cvt_pk_bf16_f32 v96, v100, v96
	v_cvt_pk_bf16_f32 v97, v97, v98
	v_cvt_pk_bf16_f32 v98, v104, v101
	v_cvt_pk_bf16_f32 v99, v102, v99
	global_store_dwordx4 v[112:113], v[96:99], off
	s_nop 1
	v_mov_b32_e32 v98, v205
	s_nop 0
	v_or_b32_e32 v96, 32, v144
	v_mad_i64_i32 v[96:97], s[40:41], v96, s52, v[146:147]
	v_lshl_add_u64 v[96:97], v[96:97], 0, v[148:149]
	v_mul_f32_e32 v99, v98, v98
	v_mul_f32_e32 v98, 0xbfb8aa3b, v98
	v_mul_f32_e32 v100, v92, v99
	v_mul_f32_e32 v101, v88, v99
	v_mul_f32_e32 v88, v88, v98
	v_mul_f32_e32 v102, v93, v99
	v_mul_f32_e32 v93, v93, v98
	v_mul_f32_e32 v103, v89, v99
	v_mul_f32_e32 v89, v89, v98
	v_mul_f32_e32 v104, v94, v99
	v_mul_f32_e32 v94, v94, v98
	v_mul_f32_e32 v105, v90, v99
	v_mul_f32_e32 v90, v90, v98
	v_mul_f32_e32 v106, v95, v99
	v_mul_f32_e32 v95, v95, v98
	v_mul_f32_e32 v99, v91, v99
	v_mul_f32_e32 v91, v91, v98
	v_mul_f32_e32 v92, v92, v98
	v_exp_f32_e32 v88, v88
	v_exp_f32_e32 v93, v93
	v_exp_f32_e32 v89, v89
	v_exp_f32_e32 v94, v94
	v_exp_f32_e32 v90, v90
	v_exp_f32_e32 v95, v95
	v_exp_f32_e32 v91, v91
	v_exp_f32_e32 v92, v92
	v_add_f32_e32 v88, 1.0, v88
	v_add_f32_e32 v93, 1.0, v93
	v_add_f32_e32 v89, 1.0, v89
	v_add_f32_e32 v94, 1.0, v94
	v_add_f32_e32 v90, 1.0, v90
	v_add_f32_e32 v95, 1.0, v95
	v_add_f32_e32 v91, 1.0, v91
	v_add_f32_e32 v92, 1.0, v92
	v_rcp_f32_e32 v88, v88
	v_rcp_f32_e32 v93, v93
	v_rcp_f32_e32 v89, v89
	v_rcp_f32_e32 v94, v94
	v_rcp_f32_e32 v90, v90
	v_rcp_f32_e32 v95, v95
	v_rcp_f32_e32 v91, v91
	v_rcp_f32_e32 v92, v92
	v_mul_f32_e32 v88, v101, v88
	v_mul_f32_e32 v93, v102, v93
	v_mul_f32_e32 v89, v103, v89
	v_mul_f32_e32 v94, v104, v94
	v_mul_f32_e32 v90, v105, v90
	v_mul_f32_e32 v95, v106, v95
	v_mul_f32_e32 v91, v99, v91
	v_mul_f32_e32 v92, v100, v92
	v_mul_f32_e32 v88, v80, v88
	v_mul_f32_e32 v80, v85, v93
	v_mul_f32_e32 v85, v81, v89
	v_mul_f32_e32 v81, v86, v94
	v_mul_f32_e32 v86, v82, v90
	v_mul_f32_e32 v82, v87, v95
	v_mul_f32_e32 v83, v83, v91
	v_mul_f32_e32 v84, v84, v92
	v_cvt_pk_bf16_f32 v80, v84, v80
	v_cvt_pk_bf16_f32 v81, v81, v82
	v_cvt_pk_bf16_f32 v82, v88, v85
	v_cvt_pk_bf16_f32 v83, v86, v83
	global_store_dwordx4 v[96:97], v[80:83], off
	s_nop 1
	v_mov_b32_e32 v82, v206
	s_nop 0
	v_or_b32_e32 v80, 48, v144
	v_mad_i64_i32 v[80:81], s[40:41], v80, s52, v[146:147]
	v_lshl_add_u64 v[80:81], v[80:81], 0, v[148:149]
	v_mul_f32_e32 v83, v82, v82
	v_mul_f32_e32 v82, 0xbfb8aa3b, v82
	v_mul_f32_e32 v84, v76, v83
	v_mul_f32_e32 v85, v72, v83
	v_mul_f32_e32 v72, v72, v82
	v_mul_f32_e32 v86, v77, v83
	v_mul_f32_e32 v77, v77, v82
	v_mul_f32_e32 v87, v73, v83
	v_mul_f32_e32 v73, v73, v82
	v_mul_f32_e32 v88, v78, v83
	v_mul_f32_e32 v78, v78, v82
	v_mul_f32_e32 v89, v74, v83
	v_mul_f32_e32 v74, v74, v82
	v_mul_f32_e32 v90, v79, v83
	v_mul_f32_e32 v79, v79, v82
	v_mul_f32_e32 v83, v75, v83
	v_mul_f32_e32 v75, v75, v82
	v_mul_f32_e32 v76, v76, v82
	v_exp_f32_e32 v72, v72
	v_exp_f32_e32 v77, v77
	v_exp_f32_e32 v73, v73
	v_exp_f32_e32 v78, v78
	v_exp_f32_e32 v74, v74
	v_exp_f32_e32 v79, v79
	v_exp_f32_e32 v75, v75
	v_exp_f32_e32 v76, v76
	v_add_f32_e32 v72, 1.0, v72
	v_add_f32_e32 v77, 1.0, v77
	v_add_f32_e32 v73, 1.0, v73
	v_add_f32_e32 v78, 1.0, v78
	v_add_f32_e32 v74, 1.0, v74
	v_add_f32_e32 v79, 1.0, v79
	v_add_f32_e32 v75, 1.0, v75
	v_add_f32_e32 v76, 1.0, v76
	v_rcp_f32_e32 v72, v72
	v_rcp_f32_e32 v77, v77
	v_rcp_f32_e32 v73, v73
	v_rcp_f32_e32 v78, v78
	v_rcp_f32_e32 v74, v74
	v_rcp_f32_e32 v79, v79
	v_rcp_f32_e32 v75, v75
	v_rcp_f32_e32 v76, v76
	v_mul_f32_e32 v72, v85, v72
	v_mul_f32_e32 v77, v86, v77
	v_mul_f32_e32 v73, v87, v73
	v_mul_f32_e32 v78, v88, v78
	v_mul_f32_e32 v74, v89, v74
	v_mul_f32_e32 v79, v90, v79
; __device__ __forceinline__ float fast_rcp(float x) { return __builtin_amdgcn_rcpf(x); }
; __device__ __forceinline__ float fast_exp2(float x) { return __builtin_amdgcn_exp2f(x); }
; __device__ __forceinline__ u32x4 pack8(f32x4 v0, f32x4 v1) { u32x4 w; w.x = cvt_pk_bf16(v0[0], v0[1]); w.y = cvt_pk_bf16(v0[2], v0[3]); w.z = cvt_pk_bf16(v1[0], v1[1]); w.w = cvt_pk_bf16(v1[2], v1[3]); return w; }
;     __device__ __forceinline__ void operator()(const f32x4 (&acc)[2][2][4][2], const Unit& u, int wr, int wc, int fr, int fq) const {
;     ...
;         for (int ai = 0; ai < 2; ++ai)
; #pragma unroll
;             for (int m = 0; m < 4; ++m) { bf16_t* rowp = O + (size_t)(row0 + ai * HALF + m * 16) * DFF + col0;
;                 const float r = rs[row0 + ai * HALF + m * 16], r2 = r * r;
;                 f32x4 h0, h1;
; #pragma unroll
;                 for (int j = 0; j < 4; ++j) {
;                     const float g0 = acc[ai][0][m][0][j], g1 = acc[ai][0][m][1][j];
;                     h0[j] = g0 * r2 * fast_rcp(1.0f + fast_exp2(g0 * (-LOG2E * r))) * acc[ai][1][m][0][j];
;                     h1[j] = g1 * r2 * fast_rcp(1.0f + fast_exp2(g1 * (-LOG2E * r))) * acc[ai][1][m][1][j]; }
;                 *(u32x4*)rowp = pack8(h0, h1); }
	v_mul_f32_e32 v75, v83, v75
	v_mul_f32_e32 v76, v84, v76
	v_mul_f32_e32 v72, v64, v72
	v_mul_f32_e32 v64, v69, v77
	v_mul_f32_e32 v69, v65, v73
	v_mul_f32_e32 v65, v70, v78
	v_mul_f32_e32 v70, v66, v74
	v_mul_f32_e32 v66, v71, v79
	v_mul_f32_e32 v67, v67, v75
	v_mul_f32_e32 v68, v68, v76
	v_cvt_pk_bf16_f32 v64, v68, v64
	v_cvt_pk_bf16_f32 v65, v65, v66
	v_cvt_pk_bf16_f32 v66, v72, v69
	v_cvt_pk_bf16_f32 v67, v70, v67
	global_store_dwordx4 v[80:81], v[64:67], off
	s_nop 1
	v_mov_b32_e32 v66, v207
	s_nop 0
	v_add_u32_e32 v64, 0x80, v144
	v_mad_i64_i32 v[64:65], s[40:41], v64, s52, v[146:147]
	v_lshl_add_u64 v[64:65], v[64:65], 0, v[148:149]
	v_mul_f32_e32 v67, v66, v66
	v_mul_f32_e32 v66, 0xbfb8aa3b, v66
	v_mul_f32_e32 v68, v60, v67
	v_mul_f32_e32 v69, v56, v67
	v_mul_f32_e32 v56, v56, v66
	v_mul_f32_e32 v70, v61, v67
	v_mul_f32_e32 v61, v61, v66
	v_mul_f32_e32 v71, v57, v67
	v_mul_f32_e32 v57, v57, v66
	v_mul_f32_e32 v72, v62, v67
	v_mul_f32_e32 v62, v62, v66
	v_mul_f32_e32 v73, v58, v67
	v_mul_f32_e32 v58, v58, v66
	v_mul_f32_e32 v74, v63, v67
	v_mul_f32_e32 v63, v63, v66
	v_mul_f32_e32 v67, v59, v67
	v_mul_f32_e32 v59, v59, v66
	v_mul_f32_e32 v60, v60, v66
	v_exp_f32_e32 v56, v56
	v_exp_f32_e32 v61, v61
	v_exp_f32_e32 v57, v57
	v_exp_f32_e32 v62, v62
	v_exp_f32_e32 v58, v58
	v_exp_f32_e32 v63, v63
	v_exp_f32_e32 v59, v59
	v_exp_f32_e32 v60, v60
	v_add_f32_e32 v56, 1.0, v56
	v_add_f32_e32 v61, 1.0, v61
	v_add_f32_e32 v57, 1.0, v57
	v_add_f32_e32 v62, 1.0, v62
	v_add_f32_e32 v58, 1.0, v58
	v_add_f32_e32 v63, 1.0, v63
	v_add_f32_e32 v59, 1.0, v59
	v_add_f32_e32 v60, 1.0, v60
	v_rcp_f32_e32 v56, v56
	v_rcp_f32_e32 v61, v61
	v_rcp_f32_e32 v57, v57
	v_rcp_f32_e32 v62, v62
	v_rcp_f32_e32 v58, v58
	v_rcp_f32_e32 v63, v63
	v_rcp_f32_e32 v59, v59
	v_rcp_f32_e32 v60, v60
	v_mul_f32_e32 v56, v69, v56
	v_mul_f32_e32 v61, v70, v61
	v_mul_f32_e32 v57, v71, v57
	v_mul_f32_e32 v62, v72, v62
	v_mul_f32_e32 v58, v73, v58
	v_mul_f32_e32 v63, v74, v63
	v_mul_f32_e32 v59, v67, v59
	v_mul_f32_e32 v60, v68, v60
	v_mul_f32_e32 v56, v48, v56
	v_mul_f32_e32 v48, v53, v61
	v_mul_f32_e32 v53, v49, v57
	v_mul_f32_e32 v49, v54, v62
	v_mul_f32_e32 v54, v50, v58
	v_mul_f32_e32 v50, v55, v63
	v_mul_f32_e32 v51, v51, v59
	v_mul_f32_e32 v52, v52, v60
	v_cvt_pk_bf16_f32 v48, v52, v48
	v_cvt_pk_bf16_f32 v49, v49, v50
	v_cvt_pk_bf16_f32 v50, v56, v53
	v_cvt_pk_bf16_f32 v51, v54, v51
	global_store_dwordx4 v[64:65], v[48:51], off
	s_nop 1
	v_mov_b32_e32 v50, v208
	s_nop 0
	v_add_u32_e32 v48, 0x90, v144
	v_mad_i64_i32 v[48:49], s[40:41], v48, s52, v[146:147]
	v_lshl_add_u64 v[48:49], v[48:49], 0, v[148:149]
	v_mul_f32_e32 v51, v50, v50
	v_mul_f32_e32 v50, 0xbfb8aa3b, v50
	v_mul_f32_e32 v52, v44, v51
	v_mul_f32_e32 v53, v40, v51
	v_mul_f32_e32 v40, v40, v50
	v_mul_f32_e32 v54, v45, v51
	v_mul_f32_e32 v45, v45, v50
	v_mul_f32_e32 v55, v41, v51
	v_mul_f32_e32 v41, v41, v50
	v_mul_f32_e32 v56, v46, v51
	v_mul_f32_e32 v46, v46, v50
	v_mul_f32_e32 v57, v42, v51
	v_mul_f32_e32 v42, v42, v50
	v_mul_f32_e32 v58, v47, v51
	v_mul_f32_e32 v47, v47, v50
	v_mul_f32_e32 v51, v43, v51
	v_mul_f32_e32 v43, v43, v50
	v_mul_f32_e32 v44, v44, v50
	v_exp_f32_e32 v40, v40
	v_exp_f32_e32 v45, v45
	v_exp_f32_e32 v41, v41
	v_exp_f32_e32 v46, v46
	v_exp_f32_e32 v42, v42
	v_exp_f32_e32 v47, v47
	v_exp_f32_e32 v43, v43
	v_exp_f32_e32 v44, v44
	v_add_f32_e32 v40, 1.0, v40
	v_add_f32_e32 v45, 1.0, v45
	v_add_f32_e32 v41, 1.0, v41
	v_add_f32_e32 v46, 1.0, v46
	v_add_f32_e32 v42, 1.0, v42
	v_add_f32_e32 v47, 1.0, v47
	v_add_f32_e32 v43, 1.0, v43
	v_add_f32_e32 v44, 1.0, v44
	v_rcp_f32_e32 v40, v40
	v_rcp_f32_e32 v45, v45
	v_rcp_f32_e32 v41, v41
	v_rcp_f32_e32 v46, v46
	v_rcp_f32_e32 v42, v42
	v_rcp_f32_e32 v47, v47
	v_rcp_f32_e32 v43, v43
	v_rcp_f32_e32 v44, v44
	v_mul_f32_e32 v40, v53, v40
	v_mul_f32_e32 v45, v54, v45
	v_mul_f32_e32 v41, v55, v41
	v_mul_f32_e32 v46, v56, v46
	v_mul_f32_e32 v42, v57, v42
	v_mul_f32_e32 v47, v58, v47
	v_mul_f32_e32 v43, v51, v43
	v_mul_f32_e32 v44, v52, v44
	v_mul_f32_e32 v40, v32, v40
	v_mul_f32_e32 v32, v37, v45
	v_mul_f32_e32 v37, v33, v41
	v_mul_f32_e32 v33, v38, v46
	v_mul_f32_e32 v38, v34, v42
	v_mul_f32_e32 v34, v39, v47
	v_mul_f32_e32 v35, v35, v43
; __device__ __forceinline__ float fast_rcp(float x) { return __builtin_amdgcn_rcpf(x); }
; __device__ __forceinline__ float fast_exp2(float x) { return __builtin_amdgcn_exp2f(x); }
; #define PG8_WAIT_V(n) asm volatile("s_waitcnt vmcnt(" #n ")" ::: "memory")
; #define PG8_BAR __builtin_amdgcn_s_barrier()
; __device__ __forceinline__ u32x4 pack8(f32x4 v0, f32x4 v1) { u32x4 w; w.x = cvt_pk_bf16(v0[0], v0[1]); w.y = cvt_pk_bf16(v0[2], v0[3]); w.z = cvt_pk_bf16(v1[0], v1[1]); w.w = cvt_pk_bf16(v1[2], v1[3]); return w; }
; template <class Epi>
; __device__ __forceinline__ void gemm_phase(LAS unsigned char* lds, const Gemm g, const StaticOrder& S, const Epi& E) {
;     ...
;         if (!has_next) break;
; #pragma unroll
;         for (int a = 0; a < 2; ++a)
; #pragma unroll
;             for (int b = 0; b < 2; ++b)
; #pragma unroll
;                 for (int m = 0; m < 4; ++m)
; #pragma unroll
;                     for (int n = 0; n < 2; ++n) acc[a][b][m][n] = (f32x4){0.f, 0.f, 0.f, 0.f};
;         cur = nxt; cA = nA; cB = nB; ++ui;
;     }
;     PG8_WAIT_V(0);
;     if (wr == 0) PG8_BAR;
;     PG8_BAR;
;     __device__ __forceinline__ void operator()(const f32x4 (&acc)[2][2][4][2], const Unit& u, int wr, int wc, int fr, int fq) const {
;     ...
;         for (int ai = 0; ai < 2; ++ai)
; #pragma unroll
;             for (int m = 0; m < 4; ++m) { bf16_t* rowp = O + (size_t)(row0 + ai * HALF + m * 16) * DFF + col0;
;                 const float r = rs[row0 + ai * HALF + m * 16], r2 = r * r;
;                 f32x4 h0, h1;
; #pragma unroll
;                 for (int j = 0; j < 4; ++j) {
;                     const float g0 = acc[ai][0][m][0][j], g1 = acc[ai][0][m][1][j];
;                     h0[j] = g0 * r2 * fast_rcp(1.0f + fast_exp2(g0 * (-LOG2E * r))) * acc[ai][1][m][0][j];
;                     h1[j] = g1 * r2 * fast_rcp(1.0f + fast_exp2(g1 * (-LOG2E * r))) * acc[ai][1][m][1][j]; }
;                 *(u32x4*)rowp = pack8(h0, h1); }
	v_mul_f32_e32 v36, v36, v44
	v_cvt_pk_bf16_f32 v32, v36, v32
	v_cvt_pk_bf16_f32 v33, v33, v34
	v_cvt_pk_bf16_f32 v34, v40, v37
	v_cvt_pk_bf16_f32 v35, v38, v35
	global_store_dwordx4 v[48:49], v[32:35], off
	s_nop 1
	v_mov_b32_e32 v34, v209
	s_nop 0
	v_add_u32_e32 v32, 0xa0, v144
	v_mad_i64_i32 v[32:33], s[40:41], v32, s52, v[146:147]
	v_lshl_add_u64 v[32:33], v[32:33], 0, v[148:149]
	s_mov_b64 s[40:41], s[34:35]
	v_mul_f32_e32 v35, v34, v34
	v_mul_f32_e32 v34, 0xbfb8aa3b, v34
	v_mul_f32_e32 v36, v28, v35
	v_mul_f32_e32 v37, v24, v35
	v_mul_f32_e32 v24, v24, v34
	v_mul_f32_e32 v38, v29, v35
	v_mul_f32_e32 v29, v29, v34
	v_mul_f32_e32 v39, v25, v35
	v_mul_f32_e32 v25, v25, v34
	v_mul_f32_e32 v40, v30, v35
	v_mul_f32_e32 v30, v30, v34
	v_mul_f32_e32 v41, v26, v35
	v_mul_f32_e32 v26, v26, v34
	v_mul_f32_e32 v42, v31, v35
	v_mul_f32_e32 v31, v31, v34
	v_mul_f32_e32 v35, v27, v35
	v_mul_f32_e32 v27, v27, v34
	v_mul_f32_e32 v28, v28, v34
	v_exp_f32_e32 v24, v24
	v_exp_f32_e32 v29, v29
	v_exp_f32_e32 v25, v25
	v_exp_f32_e32 v30, v30
	v_exp_f32_e32 v26, v26
	v_exp_f32_e32 v31, v31
	v_exp_f32_e32 v27, v27
	v_exp_f32_e32 v28, v28
	v_add_f32_e32 v24, 1.0, v24
	v_add_f32_e32 v29, 1.0, v29
	v_add_f32_e32 v25, 1.0, v25
	v_add_f32_e32 v30, 1.0, v30
	v_add_f32_e32 v26, 1.0, v26
	v_add_f32_e32 v31, 1.0, v31
	v_add_f32_e32 v27, 1.0, v27
	v_add_f32_e32 v28, 1.0, v28
	v_rcp_f32_e32 v24, v24
	v_rcp_f32_e32 v29, v29
	v_rcp_f32_e32 v25, v25
	v_rcp_f32_e32 v30, v30
	v_rcp_f32_e32 v26, v26
	v_rcp_f32_e32 v31, v31
	v_rcp_f32_e32 v27, v27
	v_rcp_f32_e32 v28, v28
	v_mul_f32_e32 v24, v37, v24
	v_mul_f32_e32 v29, v38, v29
	v_mul_f32_e32 v25, v39, v25
	v_mul_f32_e32 v30, v40, v30
	v_mul_f32_e32 v26, v41, v26
	v_mul_f32_e32 v31, v42, v31
	v_mul_f32_e32 v27, v35, v27
	v_mul_f32_e32 v28, v36, v28
	v_mul_f32_e32 v24, v16, v24
	v_mul_f32_e32 v16, v21, v29
	v_mul_f32_e32 v21, v17, v25
	v_mul_f32_e32 v17, v22, v30
	v_mul_f32_e32 v22, v18, v26
	v_mul_f32_e32 v18, v23, v31
	v_mul_f32_e32 v19, v19, v27
	v_mul_f32_e32 v20, v20, v28
	v_cvt_pk_bf16_f32 v16, v20, v16
	v_cvt_pk_bf16_f32 v17, v17, v18
	v_cvt_pk_bf16_f32 v18, v24, v21
	v_cvt_pk_bf16_f32 v19, v22, v19
	global_store_dwordx4 v[32:33], v[16:19], off
	s_nop 1
	v_mov_b32_e32 v18, v210
	s_nop 0
	v_add_u32_e32 v16, 0xb0, v144
	v_mad_i64_i32 v[16:17], s[6:7], v16, s52, v[146:147]
	v_lshl_add_u64 v[16:17], v[16:17], 0, v[148:149]
	v_mul_f32_e32 v19, v18, v18
	v_mul_f32_e32 v18, 0xbfb8aa3b, v18
	v_mul_f32_e32 v20, v12, v19
	v_mul_f32_e32 v21, v8, v19
	v_mul_f32_e32 v8, v8, v18
	v_mul_f32_e32 v22, v13, v19
	v_mul_f32_e32 v13, v13, v18
	v_mul_f32_e32 v23, v9, v19
	v_mul_f32_e32 v9, v9, v18
	v_mul_f32_e32 v24, v14, v19
	v_mul_f32_e32 v14, v14, v18
	v_mul_f32_e32 v25, v10, v19
	v_mul_f32_e32 v10, v10, v18
	v_mul_f32_e32 v26, v15, v19
	v_mul_f32_e32 v15, v15, v18
	v_mul_f32_e32 v19, v11, v19
	v_mul_f32_e32 v11, v11, v18
	v_mul_f32_e32 v12, v12, v18
	v_exp_f32_e32 v8, v8
	v_exp_f32_e32 v13, v13
	v_exp_f32_e32 v9, v9
	v_exp_f32_e32 v14, v14
	v_exp_f32_e32 v10, v10
	v_exp_f32_e32 v15, v15
	v_exp_f32_e32 v11, v11
	v_exp_f32_e32 v12, v12
	v_add_f32_e32 v8, 1.0, v8
	v_add_f32_e32 v13, 1.0, v13
	v_add_f32_e32 v9, 1.0, v9
	v_add_f32_e32 v14, 1.0, v14
	v_add_f32_e32 v10, 1.0, v10
	v_add_f32_e32 v15, 1.0, v15
	v_add_f32_e32 v11, 1.0, v11
	v_add_f32_e32 v12, 1.0, v12
	v_rcp_f32_e32 v8, v8
	v_rcp_f32_e32 v13, v13
	v_rcp_f32_e32 v9, v9
	v_rcp_f32_e32 v14, v14
	v_rcp_f32_e32 v10, v10
	v_rcp_f32_e32 v15, v15
	v_rcp_f32_e32 v11, v11
	v_rcp_f32_e32 v12, v12
	v_mul_f32_e32 v8, v21, v8
	v_mul_f32_e32 v13, v22, v13
	v_mul_f32_e32 v9, v23, v9
	v_mul_f32_e32 v14, v24, v14
	v_mul_f32_e32 v10, v25, v10
	v_mul_f32_e32 v15, v26, v15
	v_mul_f32_e32 v11, v19, v11
	v_mul_f32_e32 v12, v20, v12
	v_mul_f32_e32 v8, v0, v8
	v_mul_f32_e32 v0, v5, v13
	v_mul_f32_e32 v5, v1, v9
	v_mul_f32_e32 v1, v6, v14
	v_mul_f32_e32 v6, v2, v10
	v_mul_f32_e32 v2, v7, v15
	v_mul_f32_e32 v3, v3, v11
	v_mul_f32_e32 v4, v4, v12
	v_cvt_pk_bf16_f32 v0, v4, v0
	v_cvt_pk_bf16_f32 v1, v1, v2
	v_cvt_pk_bf16_f32 v2, v8, v5
	v_cvt_pk_bf16_f32 v3, v6, v3
	global_store_dwordx4 v[16:17], v[0:3], off
	s_cbranch_vccz .LBB0_793
	s_waitcnt vmcnt(0)
	s_cmpk_gt_u32 s10, 0xff
	s_cbranch_scc1 .LBB0_800
	s_barrier
